# EpiRes epilogues: counted per-piece waits instead of one vmcnt(0) after the residual tile loads
# speedup vs baseline: 1.0017x; 1.0017x over previous
.LBB0_546:
	v_lshl_or_b32 v2, s72, 8, v245
	v_add_u32_e32 v226, s27, v243
	v_ashrrev_i32_e32 v3, 31, v2
	v_lshlrev_b64 v[228:229], 1, v[2:3]
	v_ashrrev_i32_e32 v227, 31, v226
	v_lshl_add_u64 v[132:133], s[16:17], 0, v[228:229]
	v_lshlrev_b64 v[230:231], 11, v[226:227]
	v_lshl_add_u64 v[134:135], v[132:133], 0, v[230:231]
	global_load_dwordx4 v[234:237], v[134:135], off
	global_load_dwordx4 v[188:191], v[134:135], off offset:256
	v_or_b32_e32 v134, 16, v226
	v_ashrrev_i32_e32 v135, 31, v134
	v_lshlrev_b64 v[224:225], 11, v[134:135]
	v_lshl_add_u64 v[134:135], v[132:133], 0, v[224:225]
	global_load_dwordx4 v[184:187], v[134:135], off
	global_load_dwordx4 v[180:183], v[134:135], off offset:256
	v_or_b32_e32 v134, 32, v226
	v_ashrrev_i32_e32 v135, 31, v134
	v_lshlrev_b64 v[222:223], 11, v[134:135]
	v_lshl_add_u64 v[134:135], v[132:133], 0, v[222:223]
	global_load_dwordx4 v[176:179], v[134:135], off
	global_load_dwordx4 v[172:175], v[134:135], off offset:256
	v_or_b32_e32 v134, 48, v226
	v_ashrrev_i32_e32 v135, 31, v134
	v_lshlrev_b64 v[220:221], 11, v[134:135]
	v_lshl_add_u64 v[134:135], v[132:133], 0, v[220:221]
	v_lshl_add_u64 v[218:219], v[230:231], 0, s[88:89]
	global_load_dwordx4 v[168:171], v[134:135], off
	global_load_dwordx4 v[164:167], v[134:135], off offset:256
	v_lshl_add_u64 v[134:135], v[132:133], 0, v[218:219]
	v_lshl_add_u64 v[216:217], v[230:231], 0, s[60:61]
	global_load_dwordx4 v[160:163], v[134:135], off
	global_load_dwordx4 v[156:159], v[134:135], off offset:256
	v_lshl_add_u64 v[134:135], v[132:133], 0, v[216:217]
	v_lshl_add_u64 v[214:215], v[230:231], 0, s[62:63]
	v_lshl_add_u64 v[212:213], v[230:231], 0, s[66:67]
	global_load_dwordx4 v[152:155], v[134:135], off
	global_load_dwordx4 v[148:151], v[134:135], off offset:256
	v_lshl_add_u64 v[134:135], v[132:133], 0, v[214:215]
	v_lshl_add_u64 v[132:133], v[132:133], 0, v[212:213]
	global_load_dwordx4 v[144:147], v[134:135], off
	global_load_dwordx4 v[136:139], v[134:135], off offset:256
	global_load_dwordx4 v[140:143], v[132:133], off
	s_nop 0
	global_load_dwordx4 v[132:135], v[132:133], off offset:256
	v_lshl_add_u64 v[230:231], s[16:17], 0, v[230:231]
	v_lshl_add_u64 v[228:229], v[230:231], 0, v[228:229]
	s_waitcnt vmcnt(15)
	v_lshlrev_b32_e32 v194, 16, v234
	v_and_b32_e32 v195, 0xffff0000, v234
	v_lshlrev_b32_e32 v198, 16, v235
	v_and_b32_e32 v199, 0xffff0000, v235
	v_pk_add_f32 v[130:131], v[130:131], v[198:199]
	v_pk_add_f32 v[128:129], v[128:129], v[194:195]
	v_lshlrev_b32_e32 v194, 16, v236
	v_and_b32_e32 v195, 0xffff0000, v236
	v_lshlrev_b32_e32 v198, 16, v237
	v_and_b32_e32 v199, 0xffff0000, v237
	v_pk_add_f32 v[198:199], v[126:127], v[198:199]
	v_pk_add_f32 v[194:195], v[124:125], v[194:195]
	v_cvt_pk_bf16_f32 v124, v128, v129
	v_cvt_pk_bf16_f32 v125, v130, v131
	v_cvt_pk_bf16_f32 v126, v194, v195
	v_cvt_pk_bf16_f32 v127, v198, v199
	global_store_dwordx4 v[228:229], v[124:127], off offset:0 sc1
	s_nop 1
	v_mul_f32_e32 v0, v129, v129
	v_mul_f32_e32 v124, v131, v131
	v_fmac_f32_e32 v0, v128, v128
	v_fmac_f32_e32 v124, v130, v130
	v_add_f32_e32 v0, v0, v124
	v_mul_f32_e32 v124, v195, v195
	v_mul_f32_e32 v125, v199, v199
	v_fmac_f32_e32 v124, v194, v194
	v_fmac_f32_e32 v125, v198, v198
	v_add_f32_e32 v124, v124, v125
	v_add_f32_e32 v0, v0, v124
	s_waitcnt vmcnt(15)
	v_lshlrev_b32_e32 v124, 16, v188
	v_and_b32_e32 v125, 0xffff0000, v188
	v_lshlrev_b32_e32 v126, 16, v189
	v_and_b32_e32 v127, 0xffff0000, v189
	v_pk_add_f32 v[122:123], v[122:123], v[126:127]
	v_pk_add_f32 v[120:121], v[120:121], v[124:125]
	v_lshlrev_b32_e32 v124, 16, v190
	v_and_b32_e32 v125, 0xffff0000, v190
	v_lshlrev_b32_e32 v126, 16, v191
	v_and_b32_e32 v127, 0xffff0000, v191
	v_pk_add_f32 v[126:127], v[118:119], v[126:127]
	v_pk_add_f32 v[124:125], v[116:117], v[124:125]
	v_cvt_pk_bf16_f32 v116, v120, v121
	v_cvt_pk_bf16_f32 v117, v122, v123
	v_cvt_pk_bf16_f32 v118, v124, v125
	v_cvt_pk_bf16_f32 v119, v126, v127
	global_store_dwordx4 v[228:229], v[116:119], off offset:0x100 sc1
	s_nop 1
	v_mul_f32_e32 v116, v121, v121
	v_mul_f32_e32 v117, v123, v123
	v_fmac_f32_e32 v116, v120, v120
	v_fmac_f32_e32 v117, v122, v122
	v_add_f32_e32 v116, v116, v117
	v_mul_f32_e32 v117, v125, v125
	v_mul_f32_e32 v118, v127, v127
	v_fmac_f32_e32 v117, v124, v124
	v_fmac_f32_e32 v118, v126, v126
	v_add_f32_e32 v117, v117, v118
	v_add_f32_e32 v116, v117, v116
	v_and_b32_e32 v117, 64, v238
	v_add_f32_e32 v116, v0, v116
	v_xor_b32_e32 v0, 16, v238
	v_add_u32_e32 v117, 64, v117
	v_cmp_lt_i32_e32 vcc, v0, v117
	s_nop 1
	v_cndmask_b32_e32 v0, v238, v0, vcc
	v_lshlrev_b32_e32 v0, 2, v0
	ds_bpermute_b32 v118, v0, v116
	s_waitcnt lgkmcnt(0)
	v_add_f32_e32 v119, v116, v118
	v_xor_b32_e32 v116, 32, v238
	v_cmp_lt_i32_e32 vcc, v116, v117
	s_nop 1
	v_cndmask_b32_e32 v116, v238, v116, vcc
	v_lshlrev_b32_e32 v118, 2, v116
	ds_bpermute_b32 v120, v118, v119
	v_lshl_add_u64 v[116:117], v[226:227], 2, s[18:19]
	s_and_saveexec_b64 s[10:11], s[24:25]
	s_cbranch_execz .LBB0_548
	s_waitcnt lgkmcnt(0)
	v_add_f32_e32 v119, v119, v120
	global_atomic_add_f32 v[116:117], v119, off
.LBB0_548:
	s_or_b64 exec, exec, s[10:11]
	s_waitcnt lgkmcnt(0)
	s_waitcnt vmcnt(16)
	v_lshlrev_b32_e32 v120, 16, v184
	v_and_b32_e32 v121, 0xffff0000, v184
	v_lshlrev_b32_e32 v122, 16, v185
	v_and_b32_e32 v123, 0xffff0000, v185
	v_pk_add_f32 v[114:115], v[114:115], v[122:123]
	v_pk_add_f32 v[112:113], v[112:113], v[120:121]
	v_lshlrev_b32_e32 v120, 16, v186
	v_and_b32_e32 v121, 0xffff0000, v186
	v_lshlrev_b32_e32 v122, 16, v187
	v_and_b32_e32 v123, 0xffff0000, v187
	v_pk_add_f32 v[122:123], v[110:111], v[122:123]
	v_pk_add_f32 v[120:121], v[108:109], v[120:121]
	v_cvt_pk_bf16_f32 v108, v112, v113
	v_cvt_pk_bf16_f32 v109, v114, v115
	v_lshl_add_u64 v[124:125], s[16:17], 0, v[224:225]
	v_cvt_pk_bf16_f32 v110, v120, v121
	v_cvt_pk_bf16_f32 v111, v122, v123
	v_lshl_add_u64 v[124:125], v[2:3], 1, v[124:125]
	global_store_dwordx4 v[124:125], v[108:111], off offset:0 sc1
	s_nop 1
	v_mul_f32_e32 v108, v113, v113
	v_mul_f32_e32 v109, v115, v115
	v_fmac_f32_e32 v108, v112, v112
	v_fmac_f32_e32 v109, v114, v114
	v_add_f32_e32 v108, v108, v109
	v_mul_f32_e32 v109, v121, v121
	v_mul_f32_e32 v110, v123, v123
	v_fmac_f32_e32 v109, v120, v120
	v_fmac_f32_e32 v110, v122, v122
	v_add_f32_e32 v109, v109, v110
	v_add_f32_e32 v112, v108, v109
	s_waitcnt vmcnt(16)
	v_lshlrev_b32_e32 v108, 16, v180
	v_and_b32_e32 v109, 0xffff0000, v180
	v_lshlrev_b32_e32 v110, 16, v181
	v_and_b32_e32 v111, 0xffff0000, v181
	v_pk_add_f32 v[106:107], v[106:107], v[110:111]
	v_pk_add_f32 v[104:105], v[104:105], v[108:109]
	v_lshlrev_b32_e32 v110, 16, v183
	v_and_b32_e32 v111, 0xffff0000, v183
	v_lshlrev_b32_e32 v108, 16, v182
	v_and_b32_e32 v109, 0xffff0000, v182
	v_pk_add_f32 v[110:111], v[102:103], v[110:111]
	v_mul_f32_e32 v102, v105, v105
	v_mul_f32_e32 v103, v107, v107
	v_pk_add_f32 v[100:101], v[100:101], v[108:109]
	v_fmac_f32_e32 v102, v104, v104
	v_fmac_f32_e32 v103, v106, v106
	v_add_f32_e32 v102, v102, v103
	v_mul_f32_e32 v103, v101, v101
	v_mul_f32_e32 v108, v111, v111
	v_fmac_f32_e32 v103, v100, v100
	v_fmac_f32_e32 v108, v110, v110
	v_add_f32_e32 v103, v103, v108
	v_add_f32_e32 v102, v103, v102
	v_add_f32_e32 v108, v112, v102
	ds_bpermute_b32 v109, v0, v108
	v_cvt_pk_bf16_f32 v102, v104, v105
	v_cvt_pk_bf16_f32 v104, v100, v101
	v_cvt_pk_bf16_f32 v103, v106, v107
	v_cvt_pk_bf16_f32 v105, v110, v111
	s_waitcnt lgkmcnt(0)
	v_add_f32_e32 v100, v108, v109
	ds_bpermute_b32 v101, v118, v100
	global_store_dwordx4 v[124:125], v[102:105], off offset:0x100 sc1
	s_nop 1
	s_and_saveexec_b64 s[10:11], s[24:25]
	s_cbranch_execz .LBB0_550
	s_waitcnt lgkmcnt(0)
	v_add_f32_e32 v100, v100, v101
	global_atomic_add_f32 v[116:117], v100, off offset:64
.LBB0_550:
	s_or_b64 exec, exec, s[10:11]
	s_waitcnt vmcnt(17)
	v_lshlrev_b32_e32 v100, 16, v176
	s_waitcnt lgkmcnt(0)
	v_and_b32_e32 v101, 0xffff0000, v176
	v_lshlrev_b32_e32 v102, 16, v177
	v_and_b32_e32 v103, 0xffff0000, v177
	v_pk_add_f32 v[98:99], v[98:99], v[102:103]
	v_pk_add_f32 v[96:97], v[96:97], v[100:101]
	v_lshlrev_b32_e32 v100, 16, v178
	v_and_b32_e32 v101, 0xffff0000, v178
	v_lshlrev_b32_e32 v102, 16, v179
	v_and_b32_e32 v103, 0xffff0000, v179
	v_pk_add_f32 v[102:103], v[94:95], v[102:103]
	v_pk_add_f32 v[100:101], v[92:93], v[100:101]
	v_cvt_pk_bf16_f32 v92, v96, v97
	v_cvt_pk_bf16_f32 v93, v98, v99
	v_lshl_add_u64 v[104:105], s[16:17], 0, v[222:223]
	v_cvt_pk_bf16_f32 v94, v100, v101
	v_cvt_pk_bf16_f32 v95, v102, v103
	v_lshl_add_u64 v[104:105], v[2:3], 1, v[104:105]
	global_store_dwordx4 v[104:105], v[92:95], off offset:0 sc1
	s_nop 1
	v_mul_f32_e32 v92, v97, v97
	v_mul_f32_e32 v93, v99, v99
	v_fmac_f32_e32 v92, v96, v96
	v_fmac_f32_e32 v93, v98, v98
	v_add_f32_e32 v92, v92, v93
	v_mul_f32_e32 v93, v101, v101
	v_mul_f32_e32 v94, v103, v103
	v_fmac_f32_e32 v93, v100, v100
	v_fmac_f32_e32 v94, v102, v102
	v_add_f32_e32 v93, v93, v94
	v_add_f32_e32 v96, v92, v93
	s_waitcnt vmcnt(17)
	v_lshlrev_b32_e32 v92, 16, v172
	v_and_b32_e32 v93, 0xffff0000, v172
	v_lshlrev_b32_e32 v94, 16, v173
	v_and_b32_e32 v95, 0xffff0000, v173
	v_pk_add_f32 v[90:91], v[90:91], v[94:95]
	v_pk_add_f32 v[88:89], v[88:89], v[92:93]
	v_lshlrev_b32_e32 v94, 16, v175
	v_and_b32_e32 v95, 0xffff0000, v175
	v_lshlrev_b32_e32 v92, 16, v174
	v_and_b32_e32 v93, 0xffff0000, v174
	v_pk_add_f32 v[94:95], v[86:87], v[94:95]
	v_mul_f32_e32 v86, v89, v89
	v_mul_f32_e32 v87, v91, v91
	v_pk_add_f32 v[84:85], v[84:85], v[92:93]
	v_fmac_f32_e32 v86, v88, v88
	v_fmac_f32_e32 v87, v90, v90
	v_add_f32_e32 v86, v86, v87
	v_mul_f32_e32 v87, v85, v85
	v_mul_f32_e32 v92, v95, v95
	v_fmac_f32_e32 v87, v84, v84
	v_fmac_f32_e32 v92, v94, v94
	v_add_f32_e32 v87, v87, v92
	v_add_f32_e32 v86, v87, v86
	v_add_f32_e32 v92, v96, v86
	ds_bpermute_b32 v93, v0, v92
	v_cvt_pk_bf16_f32 v86, v88, v89
	v_cvt_pk_bf16_f32 v88, v84, v85
	v_cvt_pk_bf16_f32 v87, v90, v91
	v_cvt_pk_bf16_f32 v89, v94, v95
	s_waitcnt lgkmcnt(0)
	v_add_f32_e32 v84, v92, v93
	ds_bpermute_b32 v85, v118, v84
	global_store_dwordx4 v[104:105], v[86:89], off offset:0x100 sc1
	s_nop 1
	s_and_saveexec_b64 s[10:11], s[24:25]
	s_cbranch_execz .LBB0_552
	s_waitcnt lgkmcnt(0)
	v_add_f32_e32 v84, v84, v85
	global_atomic_add_f32 v[116:117], v84, off offset:128
.LBB0_552:
	s_or_b64 exec, exec, s[10:11]
	s_waitcnt vmcnt(18)
	v_lshlrev_b32_e32 v84, 16, v168
	s_waitcnt lgkmcnt(0)
	v_and_b32_e32 v85, 0xffff0000, v168
	v_lshlrev_b32_e32 v86, 16, v169
	v_and_b32_e32 v87, 0xffff0000, v169
	v_pk_add_f32 v[82:83], v[82:83], v[86:87]
	v_pk_add_f32 v[80:81], v[80:81], v[84:85]
	v_lshlrev_b32_e32 v84, 16, v170
	v_and_b32_e32 v85, 0xffff0000, v170
	v_lshlrev_b32_e32 v86, 16, v171
	v_and_b32_e32 v87, 0xffff0000, v171
	v_pk_add_f32 v[86:87], v[78:79], v[86:87]
	v_pk_add_f32 v[84:85], v[76:77], v[84:85]
	v_cvt_pk_bf16_f32 v76, v80, v81
	v_cvt_pk_bf16_f32 v77, v82, v83
	v_lshl_add_u64 v[88:89], s[16:17], 0, v[220:221]
	v_cvt_pk_bf16_f32 v78, v84, v85
	v_cvt_pk_bf16_f32 v79, v86, v87
	v_lshl_add_u64 v[88:89], v[2:3], 1, v[88:89]
	global_store_dwordx4 v[88:89], v[76:79], off offset:0 sc1
	s_nop 1
	v_mul_f32_e32 v76, v81, v81
	v_mul_f32_e32 v77, v83, v83
	v_fmac_f32_e32 v76, v80, v80
	v_fmac_f32_e32 v77, v82, v82
	v_add_f32_e32 v76, v76, v77
	v_mul_f32_e32 v77, v85, v85
	v_mul_f32_e32 v78, v87, v87
	v_fmac_f32_e32 v77, v84, v84
	v_fmac_f32_e32 v78, v86, v86
	v_add_f32_e32 v77, v77, v78
	v_add_f32_e32 v80, v76, v77
	s_waitcnt vmcnt(18)
	v_lshlrev_b32_e32 v76, 16, v164
	v_and_b32_e32 v77, 0xffff0000, v164
	v_lshlrev_b32_e32 v78, 16, v165
	v_and_b32_e32 v79, 0xffff0000, v165
	v_pk_add_f32 v[74:75], v[74:75], v[78:79]
	v_pk_add_f32 v[72:73], v[72:73], v[76:77]
	v_lshlrev_b32_e32 v78, 16, v167
	v_and_b32_e32 v79, 0xffff0000, v167
	v_lshlrev_b32_e32 v76, 16, v166
	v_and_b32_e32 v77, 0xffff0000, v166
	v_pk_add_f32 v[78:79], v[70:71], v[78:79]
	v_mul_f32_e32 v70, v73, v73
	v_mul_f32_e32 v71, v75, v75
	v_pk_add_f32 v[68:69], v[68:69], v[76:77]
	v_fmac_f32_e32 v70, v72, v72
	v_fmac_f32_e32 v71, v74, v74
	v_add_f32_e32 v70, v70, v71
	v_mul_f32_e32 v71, v69, v69
	v_mul_f32_e32 v76, v79, v79
	v_fmac_f32_e32 v71, v68, v68
	v_fmac_f32_e32 v76, v78, v78
	v_add_f32_e32 v71, v71, v76
	v_add_f32_e32 v70, v71, v70
	v_add_f32_e32 v76, v80, v70
	ds_bpermute_b32 v77, v0, v76
	v_cvt_pk_bf16_f32 v70, v72, v73
	v_cvt_pk_bf16_f32 v72, v68, v69
	v_cvt_pk_bf16_f32 v71, v74, v75
	v_cvt_pk_bf16_f32 v73, v78, v79
	s_waitcnt lgkmcnt(0)
	v_add_f32_e32 v68, v76, v77
	ds_bpermute_b32 v69, v118, v68
	global_store_dwordx4 v[88:89], v[70:73], off offset:0x100 sc1
	s_nop 1
	s_and_saveexec_b64 s[10:11], s[24:25]
	s_cbranch_execz .LBB0_554
	s_waitcnt lgkmcnt(0)
	v_add_f32_e32 v68, v68, v69
	global_atomic_add_f32 v[116:117], v68, off offset:192
.LBB0_554:
	s_or_b64 exec, exec, s[10:11]
	s_waitcnt vmcnt(19)
	v_lshlrev_b32_e32 v68, 16, v160
	s_waitcnt lgkmcnt(0)
	v_and_b32_e32 v69, 0xffff0000, v160
	v_lshlrev_b32_e32 v70, 16, v161
	v_and_b32_e32 v71, 0xffff0000, v161
	v_pk_add_f32 v[66:67], v[66:67], v[70:71]
	v_pk_add_f32 v[64:65], v[64:65], v[68:69]
	v_lshlrev_b32_e32 v68, 16, v162
	v_and_b32_e32 v69, 0xffff0000, v162
	v_lshlrev_b32_e32 v70, 16, v163
	v_and_b32_e32 v71, 0xffff0000, v163
	v_pk_add_f32 v[70:71], v[62:63], v[70:71]
	v_pk_add_f32 v[68:69], v[60:61], v[68:69]
	v_cvt_pk_bf16_f32 v60, v64, v65
	v_cvt_pk_bf16_f32 v61, v66, v67
	v_lshl_add_u64 v[72:73], s[16:17], 0, v[218:219]
	v_cvt_pk_bf16_f32 v62, v68, v69
	v_cvt_pk_bf16_f32 v63, v70, v71
	v_lshl_add_u64 v[72:73], v[2:3], 1, v[72:73]
	global_store_dwordx4 v[72:73], v[60:63], off offset:0 sc1
	s_nop 1
	v_mul_f32_e32 v60, v65, v65
	v_mul_f32_e32 v61, v67, v67
	v_fmac_f32_e32 v60, v64, v64
	v_fmac_f32_e32 v61, v66, v66
	v_add_f32_e32 v60, v60, v61
	v_mul_f32_e32 v61, v69, v69
	v_mul_f32_e32 v62, v71, v71
	v_fmac_f32_e32 v61, v68, v68
	v_fmac_f32_e32 v62, v70, v70
	v_add_f32_e32 v61, v61, v62
	v_add_f32_e32 v64, v60, v61
	s_waitcnt vmcnt(19)
	v_lshlrev_b32_e32 v60, 16, v156
	v_and_b32_e32 v61, 0xffff0000, v156
	v_lshlrev_b32_e32 v62, 16, v157
	v_and_b32_e32 v63, 0xffff0000, v157
	v_pk_add_f32 v[58:59], v[58:59], v[62:63]
	v_pk_add_f32 v[56:57], v[56:57], v[60:61]
	v_lshlrev_b32_e32 v62, 16, v159
	v_and_b32_e32 v63, 0xffff0000, v159
	v_lshlrev_b32_e32 v60, 16, v158
	v_and_b32_e32 v61, 0xffff0000, v158
	v_pk_add_f32 v[62:63], v[54:55], v[62:63]
	v_mul_f32_e32 v54, v57, v57
	v_mul_f32_e32 v55, v59, v59
	v_pk_add_f32 v[52:53], v[52:53], v[60:61]
	v_fmac_f32_e32 v54, v56, v56
	v_fmac_f32_e32 v55, v58, v58
	v_add_f32_e32 v54, v54, v55
	v_mul_f32_e32 v55, v53, v53
	v_mul_f32_e32 v60, v63, v63
	v_fmac_f32_e32 v55, v52, v52
	v_fmac_f32_e32 v60, v62, v62
	v_add_f32_e32 v55, v55, v60
	v_add_f32_e32 v54, v55, v54
	v_add_f32_e32 v60, v64, v54
	ds_bpermute_b32 v61, v0, v60
	v_cvt_pk_bf16_f32 v54, v56, v57
	v_cvt_pk_bf16_f32 v56, v52, v53
	v_cvt_pk_bf16_f32 v55, v58, v59
	v_cvt_pk_bf16_f32 v57, v62, v63
	s_waitcnt lgkmcnt(0)
	v_add_f32_e32 v52, v60, v61
	ds_bpermute_b32 v53, v118, v52
	global_store_dwordx4 v[72:73], v[54:57], off offset:0x100 sc1
	s_nop 1
	s_and_saveexec_b64 s[10:11], s[24:25]
	s_cbranch_execz .LBB0_556
	s_waitcnt lgkmcnt(0)
	v_add_f32_e32 v52, v52, v53
	global_atomic_add_f32 v[116:117], v52, off offset:512
.LBB0_556:
	s_or_b64 exec, exec, s[10:11]
	s_waitcnt vmcnt(20)
	v_lshlrev_b32_e32 v52, 16, v152
	s_waitcnt lgkmcnt(0)
	v_and_b32_e32 v53, 0xffff0000, v152
	v_lshlrev_b32_e32 v54, 16, v153
	v_and_b32_e32 v55, 0xffff0000, v153
	v_pk_add_f32 v[50:51], v[50:51], v[54:55]
	v_pk_add_f32 v[48:49], v[48:49], v[52:53]
	v_lshlrev_b32_e32 v52, 16, v154
	v_and_b32_e32 v53, 0xffff0000, v154
	v_lshlrev_b32_e32 v54, 16, v155
	v_and_b32_e32 v55, 0xffff0000, v155
	v_pk_add_f32 v[54:55], v[46:47], v[54:55]
	v_pk_add_f32 v[52:53], v[44:45], v[52:53]
	v_cvt_pk_bf16_f32 v44, v48, v49
	v_cvt_pk_bf16_f32 v45, v50, v51
	v_lshl_add_u64 v[56:57], s[16:17], 0, v[216:217]
	v_cvt_pk_bf16_f32 v46, v52, v53
	v_cvt_pk_bf16_f32 v47, v54, v55
	v_lshl_add_u64 v[56:57], v[2:3], 1, v[56:57]
	global_store_dwordx4 v[56:57], v[44:47], off offset:0 sc1
	s_nop 1
	v_mul_f32_e32 v44, v49, v49
	v_mul_f32_e32 v45, v51, v51
	v_fmac_f32_e32 v44, v48, v48
	v_fmac_f32_e32 v45, v50, v50
	v_add_f32_e32 v44, v44, v45
	v_mul_f32_e32 v45, v53, v53
	v_mul_f32_e32 v46, v55, v55
	v_fmac_f32_e32 v45, v52, v52
	v_fmac_f32_e32 v46, v54, v54
	v_add_f32_e32 v45, v45, v46
	v_add_f32_e32 v48, v44, v45
	s_waitcnt vmcnt(20)
	v_lshlrev_b32_e32 v44, 16, v148
	v_and_b32_e32 v45, 0xffff0000, v148
	v_lshlrev_b32_e32 v46, 16, v149
	v_and_b32_e32 v47, 0xffff0000, v149
	v_pk_add_f32 v[42:43], v[42:43], v[46:47]
	v_pk_add_f32 v[40:41], v[40:41], v[44:45]
	v_lshlrev_b32_e32 v46, 16, v151
	v_and_b32_e32 v47, 0xffff0000, v151
	v_lshlrev_b32_e32 v44, 16, v150
	v_and_b32_e32 v45, 0xffff0000, v150
	v_pk_add_f32 v[46:47], v[38:39], v[46:47]
	v_mul_f32_e32 v38, v41, v41
	v_mul_f32_e32 v39, v43, v43
	v_pk_add_f32 v[36:37], v[36:37], v[44:45]
	v_fmac_f32_e32 v38, v40, v40
	v_fmac_f32_e32 v39, v42, v42
	v_add_f32_e32 v38, v38, v39
	v_mul_f32_e32 v39, v37, v37
	v_mul_f32_e32 v44, v47, v47
	v_fmac_f32_e32 v39, v36, v36
	v_fmac_f32_e32 v44, v46, v46
	v_add_f32_e32 v39, v39, v44
	v_add_f32_e32 v38, v39, v38
	v_add_f32_e32 v44, v48, v38
	ds_bpermute_b32 v45, v0, v44
	v_cvt_pk_bf16_f32 v38, v40, v41
	v_cvt_pk_bf16_f32 v40, v36, v37
	v_cvt_pk_bf16_f32 v39, v42, v43
	v_cvt_pk_bf16_f32 v41, v46, v47
	s_waitcnt lgkmcnt(0)
	v_add_f32_e32 v36, v44, v45
	ds_bpermute_b32 v37, v118, v36
	global_store_dwordx4 v[56:57], v[38:41], off offset:0x100 sc1
	s_nop 1
	s_and_saveexec_b64 s[10:11], s[24:25]
	s_cbranch_execz .LBB0_558
	s_waitcnt lgkmcnt(0)
	v_add_f32_e32 v36, v36, v37
	global_atomic_add_f32 v[116:117], v36, off offset:576
.LBB0_558:
	s_or_b64 exec, exec, s[10:11]
	s_waitcnt vmcnt(21)
	v_lshlrev_b32_e32 v36, 16, v144
	s_waitcnt lgkmcnt(0)
	v_and_b32_e32 v37, 0xffff0000, v144
	v_lshlrev_b32_e32 v38, 16, v145
	v_and_b32_e32 v39, 0xffff0000, v145
	v_pk_add_f32 v[34:35], v[34:35], v[38:39]
	v_pk_add_f32 v[32:33], v[32:33], v[36:37]
	v_lshlrev_b32_e32 v36, 16, v146
	v_and_b32_e32 v37, 0xffff0000, v146
	v_lshlrev_b32_e32 v38, 16, v147
	v_and_b32_e32 v39, 0xffff0000, v147
	v_pk_add_f32 v[38:39], v[30:31], v[38:39]
	v_pk_add_f32 v[36:37], v[28:29], v[36:37]
	v_cvt_pk_bf16_f32 v28, v32, v33
	v_cvt_pk_bf16_f32 v29, v34, v35
	v_lshl_add_u64 v[40:41], s[16:17], 0, v[214:215]
	v_cvt_pk_bf16_f32 v30, v36, v37
	v_cvt_pk_bf16_f32 v31, v38, v39
	v_lshl_add_u64 v[40:41], v[2:3], 1, v[40:41]
	global_store_dwordx4 v[40:41], v[28:31], off offset:0 sc1
	s_nop 1
	v_mul_f32_e32 v28, v33, v33
	v_mul_f32_e32 v29, v35, v35
	v_fmac_f32_e32 v28, v32, v32
	v_fmac_f32_e32 v29, v34, v34
	v_add_f32_e32 v28, v28, v29
	v_mul_f32_e32 v29, v37, v37
	v_mul_f32_e32 v30, v39, v39
	v_fmac_f32_e32 v29, v36, v36
	v_fmac_f32_e32 v30, v38, v38
	v_add_f32_e32 v29, v29, v30
	v_add_f32_e32 v32, v28, v29
	s_waitcnt vmcnt(21)
	v_lshlrev_b32_e32 v28, 16, v136
	v_and_b32_e32 v29, 0xffff0000, v136
	v_lshlrev_b32_e32 v30, 16, v137
	v_and_b32_e32 v31, 0xffff0000, v137
	v_pk_add_f32 v[26:27], v[26:27], v[30:31]
	v_pk_add_f32 v[24:25], v[24:25], v[28:29]
	v_lshlrev_b32_e32 v30, 16, v139
	v_and_b32_e32 v31, 0xffff0000, v139
	v_lshlrev_b32_e32 v28, 16, v138
	v_and_b32_e32 v29, 0xffff0000, v138
	v_pk_add_f32 v[30:31], v[22:23], v[30:31]
	v_mul_f32_e32 v22, v25, v25
	v_mul_f32_e32 v23, v27, v27
	v_pk_add_f32 v[20:21], v[20:21], v[28:29]
	v_fmac_f32_e32 v22, v24, v24
	v_fmac_f32_e32 v23, v26, v26
	v_add_f32_e32 v22, v22, v23
	v_mul_f32_e32 v23, v21, v21
	v_mul_f32_e32 v28, v31, v31
	v_fmac_f32_e32 v23, v20, v20
	v_fmac_f32_e32 v28, v30, v30
	v_add_f32_e32 v23, v23, v28
	v_add_f32_e32 v22, v23, v22
	v_add_f32_e32 v28, v32, v22
	ds_bpermute_b32 v29, v0, v28
	v_cvt_pk_bf16_f32 v22, v24, v25
	v_cvt_pk_bf16_f32 v24, v20, v21
	v_cvt_pk_bf16_f32 v23, v26, v27
	v_cvt_pk_bf16_f32 v25, v30, v31
	s_waitcnt lgkmcnt(0)
	v_add_f32_e32 v20, v28, v29
	ds_bpermute_b32 v21, v118, v20
	global_store_dwordx4 v[40:41], v[22:25], off offset:0x100 sc1
	s_nop 1
	s_and_saveexec_b64 s[10:11], s[24:25]
	s_cbranch_execz .LBB0_560
	s_waitcnt lgkmcnt(0)
	v_add_f32_e32 v20, v20, v21
	global_atomic_add_f32 v[116:117], v20, off offset:640
.LBB0_560:
	s_or_b64 exec, exec, s[10:11]
	s_waitcnt vmcnt(22)
	v_lshlrev_b32_e32 v20, 16, v140
	s_waitcnt lgkmcnt(0)
	v_and_b32_e32 v21, 0xffff0000, v140
	v_lshlrev_b32_e32 v22, 16, v141
	v_and_b32_e32 v23, 0xffff0000, v141
	v_pk_add_f32 v[18:19], v[18:19], v[22:23]
	v_pk_add_f32 v[16:17], v[16:17], v[20:21]
	v_lshl_add_u64 v[24:25], s[16:17], 0, v[212:213]
	v_lshlrev_b32_e32 v20, 16, v142
	v_and_b32_e32 v21, 0xffff0000, v142
	v_lshlrev_b32_e32 v22, 16, v143
	v_and_b32_e32 v23, 0xffff0000, v143
	v_lshl_add_u64 v[24:25], v[2:3], 1, v[24:25]
	v_mul_f32_e32 v2, v17, v17
	v_mul_f32_e32 v3, v19, v19
	v_pk_add_f32 v[22:23], v[14:15], v[22:23]
	v_pk_add_f32 v[20:21], v[12:13], v[20:21]
	v_cvt_pk_bf16_f32 v12, v16, v17
	v_fmac_f32_e32 v2, v16, v16
	v_fmac_f32_e32 v3, v18, v18
	v_cvt_pk_bf16_f32 v13, v18, v19
	v_cvt_pk_bf16_f32 v14, v20, v21
	v_cvt_pk_bf16_f32 v15, v22, v23
	global_store_dwordx4 v[24:25], v[12:15], off offset:0 sc1
	s_nop 1
	v_add_f32_e32 v2, v2, v3
	v_mul_f32_e32 v3, v21, v21
	v_mul_f32_e32 v12, v23, v23
	v_fmac_f32_e32 v3, v20, v20
	v_fmac_f32_e32 v12, v22, v22
	v_add_f32_e32 v3, v3, v12
	v_add_f32_e32 v14, v2, v3
	s_waitcnt vmcnt(22)
	v_lshlrev_b32_e32 v2, 16, v132
	v_and_b32_e32 v3, 0xffff0000, v132
	v_lshlrev_b32_e32 v12, 16, v133
	v_and_b32_e32 v13, 0xffff0000, v133
	v_pk_add_f32 v[10:11], v[10:11], v[12:13]
	v_pk_add_f32 v[2:3], v[8:9], v[2:3]
	v_lshlrev_b32_e32 v8, 16, v134
	v_and_b32_e32 v9, 0xffff0000, v134
	v_lshlrev_b32_e32 v12, 16, v135
	v_and_b32_e32 v13, 0xffff0000, v135
	v_pk_add_f32 v[12:13], v[6:7], v[12:13]
	v_pk_add_f32 v[6:7], v[4:5], v[8:9]
	v_mul_f32_e32 v4, v3, v3
	v_mul_f32_e32 v5, v11, v11
	v_fmac_f32_e32 v4, v2, v2
	v_fmac_f32_e32 v5, v10, v10
	v_add_f32_e32 v4, v4, v5
	v_mul_f32_e32 v5, v7, v7
	v_mul_f32_e32 v8, v13, v13
	v_fmac_f32_e32 v5, v6, v6
	v_fmac_f32_e32 v8, v12, v12
	v_add_f32_e32 v5, v5, v8
	v_add_f32_e32 v4, v5, v4
	v_add_f32_e32 v8, v14, v4
	ds_bpermute_b32 v0, v0, v8
	v_cvt_pk_bf16_f32 v4, v2, v3
	v_cvt_pk_bf16_f32 v5, v10, v11
	v_cvt_pk_bf16_f32 v6, v6, v7
	v_cvt_pk_bf16_f32 v7, v12, v13
	s_waitcnt lgkmcnt(0)
	v_add_f32_e32 v0, v8, v0
	ds_bpermute_b32 v2, v118, v0
	global_store_dwordx4 v[24:25], v[4:7], off offset:0x100 sc1
	s_nop 1
	s_and_saveexec_b64 s[10:11], s[24:25]
	s_cbranch_execz .LBB0_562
	s_waitcnt lgkmcnt(0)
	v_add_f32_e32 v0, v0, v2
	global_atomic_add_f32 v[116:117], v0, off offset:704

.LBB0_590:
	v_lshl_or_b32 v2, s70, 8, v244
	v_lshl_add_u32 v226, s71, 8, v242
	v_ashrrev_i32_e32 v3, 31, v2
	v_lshlrev_b64 v[228:229], 1, v[2:3]
	v_ashrrev_i32_e32 v227, 31, v226
	v_lshl_add_u64 v[124:125], s[16:17], 0, v[228:229]
	v_lshlrev_b64 v[230:231], 11, v[226:227]
	v_lshl_add_u64 v[126:127], v[124:125], 0, v[230:231]
	global_load_dwordx4 v[234:237], v[126:127], off
	global_load_dwordx4 v[188:191], v[126:127], off offset:256
	v_or_b32_e32 v126, 16, v226
	v_ashrrev_i32_e32 v127, 31, v126
	v_lshlrev_b64 v[224:225], 11, v[126:127]
	v_lshl_add_u64 v[126:127], v[124:125], 0, v[224:225]
	global_load_dwordx4 v[184:187], v[126:127], off
	global_load_dwordx4 v[180:183], v[126:127], off offset:256
	v_or_b32_e32 v126, 32, v226
	v_ashrrev_i32_e32 v127, 31, v126
	v_lshlrev_b64 v[222:223], 11, v[126:127]
	v_lshl_add_u64 v[126:127], v[124:125], 0, v[222:223]
	global_load_dwordx4 v[176:179], v[126:127], off
	global_load_dwordx4 v[172:175], v[126:127], off offset:256
	v_or_b32_e32 v126, 48, v226
	v_ashrrev_i32_e32 v127, 31, v126
	v_lshlrev_b64 v[220:221], 11, v[126:127]
	v_lshl_add_u64 v[126:127], v[124:125], 0, v[220:221]
	v_lshl_add_u64 v[218:219], v[230:231], 0, s[88:89]
	global_load_dwordx4 v[168:171], v[126:127], off
	global_load_dwordx4 v[164:167], v[126:127], off offset:256
	v_lshl_add_u64 v[126:127], v[124:125], 0, v[218:219]
	v_lshl_add_u64 v[216:217], v[230:231], 0, s[60:61]
	global_load_dwordx4 v[160:163], v[126:127], off
	global_load_dwordx4 v[156:159], v[126:127], off offset:256
	v_lshl_add_u64 v[126:127], v[124:125], 0, v[216:217]
	v_lshl_add_u64 v[214:215], v[230:231], 0, s[62:63]
	v_lshl_add_u64 v[212:213], v[230:231], 0, s[66:67]
	global_load_dwordx4 v[152:155], v[126:127], off
	global_load_dwordx4 v[140:143], v[126:127], off offset:256
	v_lshl_add_u64 v[126:127], v[124:125], 0, v[214:215]
	v_lshl_add_u64 v[124:125], v[124:125], 0, v[212:213]
	global_load_dwordx4 v[136:139], v[126:127], off
	global_load_dwordx4 v[128:131], v[126:127], off offset:256
	global_load_dwordx4 v[132:135], v[124:125], off
	s_nop 0
	global_load_dwordx4 v[124:127], v[124:125], off offset:256
	v_lshl_add_u64 v[230:231], s[16:17], 0, v[230:231]
	v_lshl_add_u64 v[228:229], v[230:231], 0, v[228:229]
	s_waitcnt vmcnt(15)
	v_lshlrev_b32_e32 v194, 16, v234
	v_and_b32_e32 v195, 0xffff0000, v234
	v_lshlrev_b32_e32 v198, 16, v235
	v_and_b32_e32 v199, 0xffff0000, v235
	v_pk_add_f32 v[150:151], v[150:151], v[198:199]
	v_pk_add_f32 v[148:149], v[148:149], v[194:195]
	v_lshlrev_b32_e32 v194, 16, v236
	v_and_b32_e32 v195, 0xffff0000, v236
	v_lshlrev_b32_e32 v198, 16, v237
	v_and_b32_e32 v199, 0xffff0000, v237
	v_pk_add_f32 v[198:199], v[146:147], v[198:199]
	v_pk_add_f32 v[194:195], v[144:145], v[194:195]
	v_cvt_pk_bf16_f32 v144, v148, v149
	v_cvt_pk_bf16_f32 v145, v150, v151
	v_cvt_pk_bf16_f32 v146, v194, v195
	v_cvt_pk_bf16_f32 v147, v198, v199
	global_store_dwordx4 v[228:229], v[144:147], off offset:0 sc1
	s_nop 1
	v_mul_f32_e32 v0, v149, v149
	v_mul_f32_e32 v144, v151, v151
	v_fmac_f32_e32 v0, v148, v148
	v_fmac_f32_e32 v144, v150, v150
	v_add_f32_e32 v0, v0, v144
	v_mul_f32_e32 v144, v195, v195
	v_mul_f32_e32 v145, v199, v199
	v_fmac_f32_e32 v144, v194, v194
	v_fmac_f32_e32 v145, v198, v198
	v_add_f32_e32 v144, v144, v145
	v_add_f32_e32 v0, v0, v144
	s_waitcnt vmcnt(15)
	v_lshlrev_b32_e32 v144, 16, v188
	v_and_b32_e32 v145, 0xffff0000, v188
	v_lshlrev_b32_e32 v146, 16, v189
	v_and_b32_e32 v147, 0xffff0000, v189
	v_pk_add_f32 v[122:123], v[122:123], v[146:147]
	v_pk_add_f32 v[120:121], v[120:121], v[144:145]
	v_lshlrev_b32_e32 v144, 16, v190
	v_and_b32_e32 v145, 0xffff0000, v190
	v_lshlrev_b32_e32 v146, 16, v191
	v_and_b32_e32 v147, 0xffff0000, v191
	v_pk_add_f32 v[146:147], v[118:119], v[146:147]
	v_pk_add_f32 v[144:145], v[116:117], v[144:145]
	v_cvt_pk_bf16_f32 v116, v120, v121
	v_cvt_pk_bf16_f32 v117, v122, v123
	v_cvt_pk_bf16_f32 v118, v144, v145
	v_cvt_pk_bf16_f32 v119, v146, v147
	global_store_dwordx4 v[228:229], v[116:119], off offset:0x100 sc1
	s_nop 1
	v_mul_f32_e32 v116, v121, v121
	v_mul_f32_e32 v117, v123, v123
	v_fmac_f32_e32 v116, v120, v120
	v_fmac_f32_e32 v117, v122, v122
	v_add_f32_e32 v116, v116, v117
	v_mul_f32_e32 v117, v145, v145
	v_mul_f32_e32 v118, v147, v147
	v_fmac_f32_e32 v117, v144, v144
	v_fmac_f32_e32 v118, v146, v146
	v_add_f32_e32 v117, v117, v118
	v_add_f32_e32 v116, v117, v116
	v_and_b32_e32 v117, 64, v238
	v_add_f32_e32 v116, v0, v116
	v_xor_b32_e32 v0, 16, v238
	v_add_u32_e32 v117, 64, v117
	v_cmp_lt_i32_e32 vcc, v0, v117
	s_nop 1
	v_cndmask_b32_e32 v0, v238, v0, vcc
	v_lshlrev_b32_e32 v0, 2, v0
	ds_bpermute_b32 v118, v0, v116
	s_waitcnt lgkmcnt(0)
	v_add_f32_e32 v119, v116, v118
	v_xor_b32_e32 v116, 32, v238
	v_cmp_lt_i32_e32 vcc, v116, v117
	s_nop 1
	v_cndmask_b32_e32 v116, v238, v116, vcc
	v_lshlrev_b32_e32 v118, 2, v116
	ds_bpermute_b32 v120, v118, v119
	v_lshl_add_u64 v[116:117], v[226:227], 2, s[18:19]
	s_and_saveexec_b64 s[12:13], s[8:9]
	s_cbranch_execz .LBB0_592
	s_waitcnt lgkmcnt(0)
	v_add_f32_e32 v119, v119, v120
	global_atomic_add_f32 v[116:117], v119, off
.LBB0_592:
	s_or_b64 exec, exec, s[12:13]
	s_waitcnt lgkmcnt(0)
	s_waitcnt vmcnt(16)
	v_lshlrev_b32_e32 v120, 16, v184
	v_and_b32_e32 v121, 0xffff0000, v184
	v_lshlrev_b32_e32 v122, 16, v185
	v_and_b32_e32 v123, 0xffff0000, v185
	v_pk_add_f32 v[114:115], v[114:115], v[122:123]
	v_pk_add_f32 v[112:113], v[112:113], v[120:121]
	v_lshlrev_b32_e32 v120, 16, v186
	v_and_b32_e32 v121, 0xffff0000, v186
	v_lshlrev_b32_e32 v122, 16, v187
	v_and_b32_e32 v123, 0xffff0000, v187
	v_pk_add_f32 v[122:123], v[110:111], v[122:123]
	v_pk_add_f32 v[120:121], v[108:109], v[120:121]
	v_cvt_pk_bf16_f32 v108, v112, v113
	v_cvt_pk_bf16_f32 v109, v114, v115
	v_lshl_add_u64 v[144:145], s[16:17], 0, v[224:225]
	v_cvt_pk_bf16_f32 v110, v120, v121
	v_cvt_pk_bf16_f32 v111, v122, v123
	v_lshl_add_u64 v[144:145], v[2:3], 1, v[144:145]
	global_store_dwordx4 v[144:145], v[108:111], off offset:0 sc1
	s_nop 1
	v_mul_f32_e32 v108, v113, v113
	v_mul_f32_e32 v109, v115, v115
	v_fmac_f32_e32 v108, v112, v112
	v_fmac_f32_e32 v109, v114, v114
	v_add_f32_e32 v108, v108, v109
	v_mul_f32_e32 v109, v121, v121
	v_mul_f32_e32 v110, v123, v123
	v_fmac_f32_e32 v109, v120, v120
	v_fmac_f32_e32 v110, v122, v122
	v_add_f32_e32 v109, v109, v110
	v_add_f32_e32 v112, v108, v109
	s_waitcnt vmcnt(16)
	v_lshlrev_b32_e32 v108, 16, v180
	v_and_b32_e32 v109, 0xffff0000, v180
	v_lshlrev_b32_e32 v110, 16, v181
	v_and_b32_e32 v111, 0xffff0000, v181
	v_pk_add_f32 v[106:107], v[106:107], v[110:111]
	v_pk_add_f32 v[104:105], v[104:105], v[108:109]
	v_lshlrev_b32_e32 v110, 16, v183
	v_and_b32_e32 v111, 0xffff0000, v183
	v_lshlrev_b32_e32 v108, 16, v182
	v_and_b32_e32 v109, 0xffff0000, v182
	v_pk_add_f32 v[110:111], v[102:103], v[110:111]
	v_mul_f32_e32 v102, v105, v105
	v_mul_f32_e32 v103, v107, v107
	v_pk_add_f32 v[100:101], v[100:101], v[108:109]
	v_fmac_f32_e32 v102, v104, v104
	v_fmac_f32_e32 v103, v106, v106
	v_add_f32_e32 v102, v102, v103
	v_mul_f32_e32 v103, v101, v101
	v_mul_f32_e32 v108, v111, v111
	v_fmac_f32_e32 v103, v100, v100
	v_fmac_f32_e32 v108, v110, v110
	v_add_f32_e32 v103, v103, v108
	v_add_f32_e32 v102, v103, v102
	v_add_f32_e32 v108, v112, v102
	ds_bpermute_b32 v109, v0, v108
	v_cvt_pk_bf16_f32 v102, v104, v105
	v_cvt_pk_bf16_f32 v104, v100, v101
	v_cvt_pk_bf16_f32 v103, v106, v107
	v_cvt_pk_bf16_f32 v105, v110, v111
	s_waitcnt lgkmcnt(0)
	v_add_f32_e32 v100, v108, v109
	ds_bpermute_b32 v101, v118, v100
	global_store_dwordx4 v[144:145], v[102:105], off offset:0x100 sc1
	s_nop 1
	s_and_saveexec_b64 s[12:13], s[8:9]
	s_cbranch_execz .LBB0_594
	s_waitcnt lgkmcnt(0)
	v_add_f32_e32 v100, v100, v101
	global_atomic_add_f32 v[116:117], v100, off offset:64
.LBB0_594:
	s_or_b64 exec, exec, s[12:13]
	s_waitcnt vmcnt(17)
	v_lshlrev_b32_e32 v100, 16, v176
	s_waitcnt lgkmcnt(0)
	v_and_b32_e32 v101, 0xffff0000, v176
	v_lshlrev_b32_e32 v102, 16, v177
	v_and_b32_e32 v103, 0xffff0000, v177
	v_pk_add_f32 v[98:99], v[98:99], v[102:103]
	v_pk_add_f32 v[96:97], v[96:97], v[100:101]
	v_lshlrev_b32_e32 v100, 16, v178
	v_and_b32_e32 v101, 0xffff0000, v178
	v_lshlrev_b32_e32 v102, 16, v179
	v_and_b32_e32 v103, 0xffff0000, v179
	v_pk_add_f32 v[102:103], v[94:95], v[102:103]
	v_pk_add_f32 v[100:101], v[92:93], v[100:101]
	v_cvt_pk_bf16_f32 v92, v96, v97
	v_cvt_pk_bf16_f32 v93, v98, v99
	v_lshl_add_u64 v[104:105], s[16:17], 0, v[222:223]
	v_cvt_pk_bf16_f32 v94, v100, v101
	v_cvt_pk_bf16_f32 v95, v102, v103
	v_lshl_add_u64 v[104:105], v[2:3], 1, v[104:105]
	global_store_dwordx4 v[104:105], v[92:95], off offset:0 sc1
	s_nop 1
	v_mul_f32_e32 v92, v97, v97
	v_mul_f32_e32 v93, v99, v99
	v_fmac_f32_e32 v92, v96, v96
	v_fmac_f32_e32 v93, v98, v98
	v_add_f32_e32 v92, v92, v93
	v_mul_f32_e32 v93, v101, v101
	v_mul_f32_e32 v94, v103, v103
	v_fmac_f32_e32 v93, v100, v100
	v_fmac_f32_e32 v94, v102, v102
	v_add_f32_e32 v93, v93, v94
	v_add_f32_e32 v96, v92, v93
	s_waitcnt vmcnt(17)
	v_lshlrev_b32_e32 v92, 16, v172
	v_and_b32_e32 v93, 0xffff0000, v172
	v_lshlrev_b32_e32 v94, 16, v173
	v_and_b32_e32 v95, 0xffff0000, v173
	v_pk_add_f32 v[90:91], v[90:91], v[94:95]
	v_pk_add_f32 v[88:89], v[88:89], v[92:93]
	v_lshlrev_b32_e32 v94, 16, v175
	v_and_b32_e32 v95, 0xffff0000, v175
	v_lshlrev_b32_e32 v92, 16, v174
	v_and_b32_e32 v93, 0xffff0000, v174
	v_pk_add_f32 v[94:95], v[86:87], v[94:95]
	v_mul_f32_e32 v86, v89, v89
	v_mul_f32_e32 v87, v91, v91
	v_pk_add_f32 v[84:85], v[84:85], v[92:93]
	v_fmac_f32_e32 v86, v88, v88
	v_fmac_f32_e32 v87, v90, v90
	v_add_f32_e32 v86, v86, v87
	v_mul_f32_e32 v87, v85, v85
	v_mul_f32_e32 v92, v95, v95
	v_fmac_f32_e32 v87, v84, v84
	v_fmac_f32_e32 v92, v94, v94
	v_add_f32_e32 v87, v87, v92
	v_add_f32_e32 v86, v87, v86
	v_add_f32_e32 v92, v96, v86
	ds_bpermute_b32 v93, v0, v92
	v_cvt_pk_bf16_f32 v86, v88, v89
	v_cvt_pk_bf16_f32 v88, v84, v85
	v_cvt_pk_bf16_f32 v87, v90, v91
	v_cvt_pk_bf16_f32 v89, v94, v95
	s_waitcnt lgkmcnt(0)
	v_add_f32_e32 v84, v92, v93
	ds_bpermute_b32 v85, v118, v84
	global_store_dwordx4 v[104:105], v[86:89], off offset:0x100 sc1
	s_nop 1
	s_and_saveexec_b64 s[12:13], s[8:9]
	s_cbranch_execz .LBB0_596
	s_waitcnt lgkmcnt(0)
	v_add_f32_e32 v84, v84, v85
	global_atomic_add_f32 v[116:117], v84, off offset:128
.LBB0_596:
	s_or_b64 exec, exec, s[12:13]
	s_waitcnt vmcnt(18)
	v_lshlrev_b32_e32 v84, 16, v168
	s_waitcnt lgkmcnt(0)
	v_and_b32_e32 v85, 0xffff0000, v168
	v_lshlrev_b32_e32 v86, 16, v169
	v_and_b32_e32 v87, 0xffff0000, v169
	v_pk_add_f32 v[82:83], v[82:83], v[86:87]
	v_pk_add_f32 v[80:81], v[80:81], v[84:85]
	v_lshlrev_b32_e32 v84, 16, v170
	v_and_b32_e32 v85, 0xffff0000, v170
	v_lshlrev_b32_e32 v86, 16, v171
	v_and_b32_e32 v87, 0xffff0000, v171
	v_pk_add_f32 v[86:87], v[78:79], v[86:87]
	v_pk_add_f32 v[84:85], v[76:77], v[84:85]
	v_cvt_pk_bf16_f32 v76, v80, v81
	v_cvt_pk_bf16_f32 v77, v82, v83
	v_lshl_add_u64 v[88:89], s[16:17], 0, v[220:221]
	v_cvt_pk_bf16_f32 v78, v84, v85
	v_cvt_pk_bf16_f32 v79, v86, v87
	v_lshl_add_u64 v[88:89], v[2:3], 1, v[88:89]
	global_store_dwordx4 v[88:89], v[76:79], off offset:0 sc1
	s_nop 1
	v_mul_f32_e32 v76, v81, v81
	v_mul_f32_e32 v77, v83, v83
	v_fmac_f32_e32 v76, v80, v80
	v_fmac_f32_e32 v77, v82, v82
	v_add_f32_e32 v76, v76, v77
	v_mul_f32_e32 v77, v85, v85
	v_mul_f32_e32 v78, v87, v87
	v_fmac_f32_e32 v77, v84, v84
	v_fmac_f32_e32 v78, v86, v86
	v_add_f32_e32 v77, v77, v78
	v_add_f32_e32 v80, v76, v77
	s_waitcnt vmcnt(18)
	v_lshlrev_b32_e32 v76, 16, v164
	v_and_b32_e32 v77, 0xffff0000, v164
	v_lshlrev_b32_e32 v78, 16, v165
	v_and_b32_e32 v79, 0xffff0000, v165
	v_pk_add_f32 v[74:75], v[74:75], v[78:79]
	v_pk_add_f32 v[72:73], v[72:73], v[76:77]
	v_lshlrev_b32_e32 v78, 16, v167
	v_and_b32_e32 v79, 0xffff0000, v167
	v_lshlrev_b32_e32 v76, 16, v166
	v_and_b32_e32 v77, 0xffff0000, v166
	v_pk_add_f32 v[78:79], v[70:71], v[78:79]
	v_mul_f32_e32 v70, v73, v73
	v_mul_f32_e32 v71, v75, v75
	v_pk_add_f32 v[68:69], v[68:69], v[76:77]
	v_fmac_f32_e32 v70, v72, v72
	v_fmac_f32_e32 v71, v74, v74
	v_add_f32_e32 v70, v70, v71
	v_mul_f32_e32 v71, v69, v69
	v_mul_f32_e32 v76, v79, v79
	v_fmac_f32_e32 v71, v68, v68
	v_fmac_f32_e32 v76, v78, v78
	v_add_f32_e32 v71, v71, v76
	v_add_f32_e32 v70, v71, v70
	v_add_f32_e32 v76, v80, v70
	ds_bpermute_b32 v77, v0, v76
	v_cvt_pk_bf16_f32 v70, v72, v73
	v_cvt_pk_bf16_f32 v72, v68, v69
	v_cvt_pk_bf16_f32 v71, v74, v75
	v_cvt_pk_bf16_f32 v73, v78, v79
	s_waitcnt lgkmcnt(0)
	v_add_f32_e32 v68, v76, v77
	ds_bpermute_b32 v69, v118, v68
	global_store_dwordx4 v[88:89], v[70:73], off offset:0x100 sc1
	s_nop 1
	s_and_saveexec_b64 s[12:13], s[8:9]
	s_cbranch_execz .LBB0_598
	s_waitcnt lgkmcnt(0)
	v_add_f32_e32 v68, v68, v69
	global_atomic_add_f32 v[116:117], v68, off offset:192
.LBB0_598:
	s_or_b64 exec, exec, s[12:13]
	s_waitcnt vmcnt(19)
	v_lshlrev_b32_e32 v68, 16, v160
	s_waitcnt lgkmcnt(0)
	v_and_b32_e32 v69, 0xffff0000, v160
	v_lshlrev_b32_e32 v70, 16, v161
	v_and_b32_e32 v71, 0xffff0000, v161
	v_pk_add_f32 v[66:67], v[66:67], v[70:71]
	v_pk_add_f32 v[64:65], v[64:65], v[68:69]
	v_lshlrev_b32_e32 v68, 16, v162
	v_and_b32_e32 v69, 0xffff0000, v162
	v_lshlrev_b32_e32 v70, 16, v163
	v_and_b32_e32 v71, 0xffff0000, v163
	v_pk_add_f32 v[70:71], v[62:63], v[70:71]
	v_pk_add_f32 v[68:69], v[60:61], v[68:69]
	v_cvt_pk_bf16_f32 v60, v64, v65
	v_cvt_pk_bf16_f32 v61, v66, v67
	v_lshl_add_u64 v[72:73], s[16:17], 0, v[218:219]
	v_cvt_pk_bf16_f32 v62, v68, v69
	v_cvt_pk_bf16_f32 v63, v70, v71
	v_lshl_add_u64 v[72:73], v[2:3], 1, v[72:73]
	global_store_dwordx4 v[72:73], v[60:63], off offset:0 sc1
	s_nop 1
	v_mul_f32_e32 v60, v65, v65
	v_mul_f32_e32 v61, v67, v67
	v_fmac_f32_e32 v60, v64, v64
	v_fmac_f32_e32 v61, v66, v66
	v_add_f32_e32 v60, v60, v61
	v_mul_f32_e32 v61, v69, v69
	v_mul_f32_e32 v62, v71, v71
	v_fmac_f32_e32 v61, v68, v68
	v_fmac_f32_e32 v62, v70, v70
	v_add_f32_e32 v61, v61, v62
	v_add_f32_e32 v64, v60, v61
	s_waitcnt vmcnt(19)
	v_lshlrev_b32_e32 v60, 16, v156
	v_and_b32_e32 v61, 0xffff0000, v156
	v_lshlrev_b32_e32 v62, 16, v157
	v_and_b32_e32 v63, 0xffff0000, v157
	v_pk_add_f32 v[58:59], v[58:59], v[62:63]
	v_pk_add_f32 v[56:57], v[56:57], v[60:61]
	v_lshlrev_b32_e32 v62, 16, v159
	v_and_b32_e32 v63, 0xffff0000, v159
	v_lshlrev_b32_e32 v60, 16, v158
	v_and_b32_e32 v61, 0xffff0000, v158
	v_pk_add_f32 v[62:63], v[54:55], v[62:63]
	v_mul_f32_e32 v54, v57, v57
	v_mul_f32_e32 v55, v59, v59
	v_pk_add_f32 v[52:53], v[52:53], v[60:61]
	v_fmac_f32_e32 v54, v56, v56
	v_fmac_f32_e32 v55, v58, v58
	v_add_f32_e32 v54, v54, v55
	v_mul_f32_e32 v55, v53, v53
	v_mul_f32_e32 v60, v63, v63
	v_fmac_f32_e32 v55, v52, v52
	v_fmac_f32_e32 v60, v62, v62
	v_add_f32_e32 v55, v55, v60
	v_add_f32_e32 v54, v55, v54
	v_add_f32_e32 v60, v64, v54
	ds_bpermute_b32 v61, v0, v60
	v_cvt_pk_bf16_f32 v54, v56, v57
	v_cvt_pk_bf16_f32 v56, v52, v53
	v_cvt_pk_bf16_f32 v55, v58, v59
	v_cvt_pk_bf16_f32 v57, v62, v63
	s_waitcnt lgkmcnt(0)
	v_add_f32_e32 v52, v60, v61
	ds_bpermute_b32 v53, v118, v52
	global_store_dwordx4 v[72:73], v[54:57], off offset:0x100 sc1
	s_nop 1
	s_and_saveexec_b64 s[12:13], s[8:9]
	s_cbranch_execz .LBB0_600
	s_waitcnt lgkmcnt(0)
	v_add_f32_e32 v52, v52, v53
	global_atomic_add_f32 v[116:117], v52, off offset:512
.LBB0_600:
	s_or_b64 exec, exec, s[12:13]
	s_waitcnt vmcnt(20)
	v_lshlrev_b32_e32 v52, 16, v152
	s_waitcnt lgkmcnt(0)
	v_and_b32_e32 v53, 0xffff0000, v152
	v_lshlrev_b32_e32 v54, 16, v153
	v_and_b32_e32 v55, 0xffff0000, v153
	v_pk_add_f32 v[50:51], v[50:51], v[54:55]
	v_pk_add_f32 v[48:49], v[48:49], v[52:53]
	v_lshlrev_b32_e32 v52, 16, v154
	v_and_b32_e32 v53, 0xffff0000, v154
	v_lshlrev_b32_e32 v54, 16, v155
	v_and_b32_e32 v55, 0xffff0000, v155
	v_pk_add_f32 v[54:55], v[46:47], v[54:55]
	v_pk_add_f32 v[52:53], v[44:45], v[52:53]
	v_cvt_pk_bf16_f32 v44, v48, v49
	v_cvt_pk_bf16_f32 v45, v50, v51
	v_lshl_add_u64 v[56:57], s[16:17], 0, v[216:217]
	v_cvt_pk_bf16_f32 v46, v52, v53
	v_cvt_pk_bf16_f32 v47, v54, v55
	v_lshl_add_u64 v[56:57], v[2:3], 1, v[56:57]
	global_store_dwordx4 v[56:57], v[44:47], off offset:0 sc1
	s_nop 1
	v_mul_f32_e32 v44, v49, v49
	v_mul_f32_e32 v45, v51, v51
	v_fmac_f32_e32 v44, v48, v48
	v_fmac_f32_e32 v45, v50, v50
	v_add_f32_e32 v44, v44, v45
	v_mul_f32_e32 v45, v53, v53
	v_mul_f32_e32 v46, v55, v55
	v_fmac_f32_e32 v45, v52, v52
	v_fmac_f32_e32 v46, v54, v54
	v_add_f32_e32 v45, v45, v46
	v_add_f32_e32 v48, v44, v45
	s_waitcnt vmcnt(20)
	v_lshlrev_b32_e32 v44, 16, v140
	v_and_b32_e32 v45, 0xffff0000, v140
	v_lshlrev_b32_e32 v46, 16, v141
	v_and_b32_e32 v47, 0xffff0000, v141
	v_pk_add_f32 v[42:43], v[42:43], v[46:47]
	v_pk_add_f32 v[40:41], v[40:41], v[44:45]
	v_lshlrev_b32_e32 v46, 16, v143
	v_and_b32_e32 v47, 0xffff0000, v143
	v_lshlrev_b32_e32 v44, 16, v142
	v_and_b32_e32 v45, 0xffff0000, v142
	v_pk_add_f32 v[46:47], v[38:39], v[46:47]
	v_mul_f32_e32 v38, v41, v41
	v_mul_f32_e32 v39, v43, v43
	v_pk_add_f32 v[36:37], v[36:37], v[44:45]
	v_fmac_f32_e32 v38, v40, v40
	v_fmac_f32_e32 v39, v42, v42
	v_add_f32_e32 v38, v38, v39
	v_mul_f32_e32 v39, v37, v37
	v_mul_f32_e32 v44, v47, v47
	v_fmac_f32_e32 v39, v36, v36
	v_fmac_f32_e32 v44, v46, v46
	v_add_f32_e32 v39, v39, v44
	v_add_f32_e32 v38, v39, v38
	v_add_f32_e32 v44, v48, v38
	ds_bpermute_b32 v45, v0, v44
	v_cvt_pk_bf16_f32 v38, v40, v41
	v_cvt_pk_bf16_f32 v40, v36, v37
	v_cvt_pk_bf16_f32 v39, v42, v43
	v_cvt_pk_bf16_f32 v41, v46, v47
	s_waitcnt lgkmcnt(0)
	v_add_f32_e32 v36, v44, v45
	ds_bpermute_b32 v37, v118, v36
	global_store_dwordx4 v[56:57], v[38:41], off offset:0x100 sc1
	s_nop 1
	s_and_saveexec_b64 s[12:13], s[8:9]
	s_cbranch_execz .LBB0_602
	s_waitcnt lgkmcnt(0)
	v_add_f32_e32 v36, v36, v37
	global_atomic_add_f32 v[116:117], v36, off offset:576
.LBB0_602:
	s_or_b64 exec, exec, s[12:13]
	s_waitcnt vmcnt(21)
	v_lshlrev_b32_e32 v36, 16, v136
	s_waitcnt lgkmcnt(0)
	v_and_b32_e32 v37, 0xffff0000, v136
	v_lshlrev_b32_e32 v38, 16, v137
	v_and_b32_e32 v39, 0xffff0000, v137
	v_pk_add_f32 v[34:35], v[34:35], v[38:39]
	v_pk_add_f32 v[32:33], v[32:33], v[36:37]
	v_lshlrev_b32_e32 v36, 16, v138
	v_and_b32_e32 v37, 0xffff0000, v138
	v_lshlrev_b32_e32 v38, 16, v139
	v_and_b32_e32 v39, 0xffff0000, v139
	v_pk_add_f32 v[38:39], v[30:31], v[38:39]
	v_pk_add_f32 v[36:37], v[28:29], v[36:37]
	v_cvt_pk_bf16_f32 v28, v32, v33
	v_cvt_pk_bf16_f32 v29, v34, v35
	v_lshl_add_u64 v[40:41], s[16:17], 0, v[214:215]
	v_cvt_pk_bf16_f32 v30, v36, v37
	v_cvt_pk_bf16_f32 v31, v38, v39
	v_lshl_add_u64 v[40:41], v[2:3], 1, v[40:41]
	global_store_dwordx4 v[40:41], v[28:31], off offset:0 sc1
	s_nop 1
	v_mul_f32_e32 v28, v33, v33
	v_mul_f32_e32 v29, v35, v35
	v_fmac_f32_e32 v28, v32, v32
	v_fmac_f32_e32 v29, v34, v34
	v_add_f32_e32 v28, v28, v29
	v_mul_f32_e32 v29, v37, v37
	v_mul_f32_e32 v30, v39, v39
	v_fmac_f32_e32 v29, v36, v36
	v_fmac_f32_e32 v30, v38, v38
	v_add_f32_e32 v29, v29, v30
	v_add_f32_e32 v32, v28, v29
	s_waitcnt vmcnt(21)
	v_lshlrev_b32_e32 v28, 16, v128
	v_and_b32_e32 v29, 0xffff0000, v128
	v_lshlrev_b32_e32 v30, 16, v129
	v_and_b32_e32 v31, 0xffff0000, v129
	v_pk_add_f32 v[26:27], v[26:27], v[30:31]
	v_pk_add_f32 v[24:25], v[24:25], v[28:29]
	v_lshlrev_b32_e32 v30, 16, v131
	v_and_b32_e32 v31, 0xffff0000, v131
	v_lshlrev_b32_e32 v28, 16, v130
	v_and_b32_e32 v29, 0xffff0000, v130
	v_pk_add_f32 v[30:31], v[22:23], v[30:31]
	v_mul_f32_e32 v22, v25, v25
	v_mul_f32_e32 v23, v27, v27
	v_pk_add_f32 v[20:21], v[20:21], v[28:29]
	v_fmac_f32_e32 v22, v24, v24
	v_fmac_f32_e32 v23, v26, v26
	v_add_f32_e32 v22, v22, v23
	v_mul_f32_e32 v23, v21, v21
	v_mul_f32_e32 v28, v31, v31
	v_fmac_f32_e32 v23, v20, v20
	v_fmac_f32_e32 v28, v30, v30
	v_add_f32_e32 v23, v23, v28
	v_add_f32_e32 v22, v23, v22
	v_add_f32_e32 v28, v32, v22
	ds_bpermute_b32 v29, v0, v28
	v_cvt_pk_bf16_f32 v22, v24, v25
	v_cvt_pk_bf16_f32 v24, v20, v21
	v_cvt_pk_bf16_f32 v23, v26, v27
	v_cvt_pk_bf16_f32 v25, v30, v31
	s_waitcnt lgkmcnt(0)
	v_add_f32_e32 v20, v28, v29
	ds_bpermute_b32 v21, v118, v20
	global_store_dwordx4 v[40:41], v[22:25], off offset:0x100 sc1
	s_nop 1
	s_and_saveexec_b64 s[12:13], s[8:9]
	s_cbranch_execz .LBB0_604
	s_waitcnt lgkmcnt(0)
	v_add_f32_e32 v20, v20, v21
	global_atomic_add_f32 v[116:117], v20, off offset:640
.LBB0_604:
	s_or_b64 exec, exec, s[12:13]
	s_waitcnt vmcnt(22)
	v_lshlrev_b32_e32 v20, 16, v132
	s_waitcnt lgkmcnt(0)
	v_and_b32_e32 v21, 0xffff0000, v132
	v_lshlrev_b32_e32 v22, 16, v133
	v_and_b32_e32 v23, 0xffff0000, v133
	v_pk_add_f32 v[18:19], v[18:19], v[22:23]
	v_pk_add_f32 v[16:17], v[16:17], v[20:21]
	v_lshl_add_u64 v[24:25], s[16:17], 0, v[212:213]
	v_lshlrev_b32_e32 v20, 16, v134
	v_and_b32_e32 v21, 0xffff0000, v134
	v_lshlrev_b32_e32 v22, 16, v135
	v_and_b32_e32 v23, 0xffff0000, v135
	v_lshl_add_u64 v[24:25], v[2:3], 1, v[24:25]
	v_mul_f32_e32 v2, v17, v17
	v_mul_f32_e32 v3, v19, v19
	v_pk_add_f32 v[22:23], v[14:15], v[22:23]
	v_pk_add_f32 v[20:21], v[12:13], v[20:21]
	v_cvt_pk_bf16_f32 v12, v16, v17
	v_fmac_f32_e32 v2, v16, v16
	v_fmac_f32_e32 v3, v18, v18
	v_cvt_pk_bf16_f32 v13, v18, v19
	v_cvt_pk_bf16_f32 v14, v20, v21
	v_cvt_pk_bf16_f32 v15, v22, v23
	global_store_dwordx4 v[24:25], v[12:15], off offset:0 sc1
	s_nop 1
	v_add_f32_e32 v2, v2, v3
	v_mul_f32_e32 v3, v21, v21
	v_mul_f32_e32 v12, v23, v23
	v_fmac_f32_e32 v3, v20, v20
	v_fmac_f32_e32 v12, v22, v22
	v_add_f32_e32 v3, v3, v12
	v_add_f32_e32 v14, v2, v3
	s_waitcnt vmcnt(22)
	v_lshlrev_b32_e32 v2, 16, v124
	v_and_b32_e32 v3, 0xffff0000, v124
	v_lshlrev_b32_e32 v12, 16, v125
	v_and_b32_e32 v13, 0xffff0000, v125
	v_pk_add_f32 v[10:11], v[10:11], v[12:13]
	v_pk_add_f32 v[2:3], v[8:9], v[2:3]
	v_lshlrev_b32_e32 v8, 16, v126
	v_and_b32_e32 v9, 0xffff0000, v126
	v_lshlrev_b32_e32 v12, 16, v127
	v_and_b32_e32 v13, 0xffff0000, v127
	v_pk_add_f32 v[12:13], v[6:7], v[12:13]
	v_pk_add_f32 v[6:7], v[4:5], v[8:9]
	v_mul_f32_e32 v4, v3, v3
	v_mul_f32_e32 v5, v11, v11
	v_fmac_f32_e32 v4, v2, v2
	v_fmac_f32_e32 v5, v10, v10
	v_add_f32_e32 v4, v4, v5
	v_mul_f32_e32 v5, v7, v7
	v_mul_f32_e32 v8, v13, v13
	v_fmac_f32_e32 v5, v6, v6
	v_fmac_f32_e32 v8, v12, v12
	v_add_f32_e32 v5, v5, v8
	v_add_f32_e32 v4, v5, v4
	v_add_f32_e32 v8, v14, v4
	ds_bpermute_b32 v0, v0, v8
	v_cvt_pk_bf16_f32 v4, v2, v3
	v_cvt_pk_bf16_f32 v5, v10, v11
	v_cvt_pk_bf16_f32 v6, v6, v7
	v_cvt_pk_bf16_f32 v7, v12, v13
	s_waitcnt lgkmcnt(0)
	v_add_f32_e32 v0, v8, v0
	ds_bpermute_b32 v2, v118, v0
	global_store_dwordx4 v[24:25], v[4:7], off offset:0x100 sc1
	s_nop 1
	s_and_saveexec_b64 s[12:13], s[8:9]
	s_cbranch_execz .LBB0_606
	s_waitcnt lgkmcnt(0)
	v_add_f32_e32 v0, v0, v2
	global_atomic_add_f32 v[116:117], v0, off offset:704

.LBB0_776:
	v_lshl_or_b32 v208, s71, 8, v241
	v_lshl_add_u32 v224, s72, 8, v230
	v_ashrrev_i32_e32 v209, 31, v208
	v_lshlrev_b64 v[226:227], 1, v[208:209]
	v_ashrrev_i32_e32 v225, 31, v224
	v_lshl_add_u64 v[118:119], s[14:15], 0, v[226:227]
	v_lshlrev_b64 v[228:229], 11, v[224:225]
	v_lshl_add_u64 v[120:121], v[118:119], 0, v[228:229]
	global_load_dwordx4 v[234:237], v[120:121], off
	global_load_dwordx4 v[186:189], v[120:121], off offset:256
	v_or_b32_e32 v120, 16, v224
	v_ashrrev_i32_e32 v121, 31, v120
	v_lshlrev_b64 v[222:223], 11, v[120:121]
	v_lshl_add_u64 v[120:121], v[118:119], 0, v[222:223]
	global_load_dwordx4 v[182:185], v[120:121], off
	global_load_dwordx4 v[178:181], v[120:121], off offset:256
	v_or_b32_e32 v120, 32, v224
	v_ashrrev_i32_e32 v121, 31, v120
	v_lshlrev_b64 v[220:221], 11, v[120:121]
	v_lshl_add_u64 v[120:121], v[118:119], 0, v[220:221]
	global_load_dwordx4 v[174:177], v[120:121], off
	global_load_dwordx4 v[170:173], v[120:121], off offset:256
	v_or_b32_e32 v120, 48, v224
	v_ashrrev_i32_e32 v121, 31, v120
	v_lshlrev_b64 v[218:219], 11, v[120:121]
	v_lshl_add_u64 v[120:121], v[118:119], 0, v[218:219]
	v_lshl_add_u64 v[216:217], v[228:229], 0, s[88:89]
	global_load_dwordx4 v[166:169], v[120:121], off
	global_load_dwordx4 v[162:165], v[120:121], off offset:256
	v_lshl_add_u64 v[120:121], v[118:119], 0, v[216:217]
	v_lshl_add_u64 v[214:215], v[228:229], 0, s[60:61]
	global_load_dwordx4 v[158:161], v[120:121], off
	global_load_dwordx4 v[146:149], v[120:121], off offset:256
	v_lshl_add_u64 v[120:121], v[118:119], 0, v[214:215]
	v_lshl_add_u64 v[212:213], v[228:229], 0, s[62:63]
	v_lshl_add_u64 v[210:211], v[228:229], 0, s[66:67]
	global_load_dwordx4 v[142:145], v[120:121], off
	global_load_dwordx4 v[138:141], v[120:121], off offset:256
	v_lshl_add_u64 v[120:121], v[118:119], 0, v[212:213]
	v_lshl_add_u64 v[118:119], v[118:119], 0, v[210:211]
	global_load_dwordx4 v[134:137], v[120:121], off
	global_load_dwordx4 v[126:129], v[120:121], off offset:256
	global_load_dwordx4 v[130:133], v[118:119], off
	s_nop 0
	global_load_dwordx4 v[118:121], v[118:119], off offset:256
	v_lshl_add_u64 v[228:229], s[14:15], 0, v[228:229]
	v_lshl_add_u64 v[226:227], v[228:229], 0, v[226:227]
	s_waitcnt vmcnt(15)
	v_lshlrev_b32_e32 v194, 16, v234
	v_and_b32_e32 v195, 0xffff0000, v234
	v_lshlrev_b32_e32 v198, 16, v235
	v_and_b32_e32 v199, 0xffff0000, v235
	v_pk_add_f32 v[156:157], v[156:157], v[198:199]
	v_pk_add_f32 v[154:155], v[154:155], v[194:195]
	v_lshlrev_b32_e32 v194, 16, v236
	v_and_b32_e32 v195, 0xffff0000, v236
	v_lshlrev_b32_e32 v198, 16, v237
	v_and_b32_e32 v199, 0xffff0000, v237
	v_pk_add_f32 v[198:199], v[152:153], v[198:199]
	v_pk_add_f32 v[194:195], v[150:151], v[194:195]
	v_cvt_pk_bf16_f32 v150, v154, v155
	v_cvt_pk_bf16_f32 v151, v156, v157
	v_cvt_pk_bf16_f32 v152, v194, v195
	v_cvt_pk_bf16_f32 v153, v198, v199
	global_store_dwordx4 v[226:227], v[150:153], off offset:0 sc1
	s_nop 1
	v_mul_f32_e32 v150, v155, v155
	v_mul_f32_e32 v151, v157, v157
	v_fmac_f32_e32 v150, v154, v154
	v_fmac_f32_e32 v151, v156, v156
	v_add_f32_e32 v150, v150, v151
	v_mul_f32_e32 v151, v195, v195
	v_mul_f32_e32 v152, v199, v199
	v_fmac_f32_e32 v151, v194, v194
	v_fmac_f32_e32 v152, v198, v198
	v_add_f32_e32 v151, v151, v152
	v_add_f32_e32 v154, v150, v151
	s_waitcnt vmcnt(15)
	v_lshlrev_b32_e32 v150, 16, v186
	v_and_b32_e32 v151, 0xffff0000, v186
	v_lshlrev_b32_e32 v152, 16, v187
	v_and_b32_e32 v153, 0xffff0000, v187
	v_pk_add_f32 v[124:125], v[124:125], v[152:153]
	v_pk_add_f32 v[122:123], v[122:123], v[150:151]
	v_lshlrev_b32_e32 v150, 16, v188
	v_and_b32_e32 v151, 0xffff0000, v188
	v_lshlrev_b32_e32 v152, 16, v189
	v_and_b32_e32 v153, 0xffff0000, v189
	v_pk_add_f32 v[152:153], v[116:117], v[152:153]
	v_pk_add_f32 v[150:151], v[114:115], v[150:151]
	v_cvt_pk_bf16_f32 v114, v122, v123
	v_cvt_pk_bf16_f32 v115, v124, v125
	v_cvt_pk_bf16_f32 v116, v150, v151
	v_cvt_pk_bf16_f32 v117, v152, v153
	global_store_dwordx4 v[226:227], v[114:117], off offset:0x100 sc1
	s_nop 1
	v_mul_f32_e32 v114, v123, v123
	v_mul_f32_e32 v115, v125, v125
	v_fmac_f32_e32 v114, v122, v122
	v_fmac_f32_e32 v115, v124, v124
	v_add_f32_e32 v114, v114, v115
	v_mul_f32_e32 v115, v151, v151
	v_mul_f32_e32 v116, v153, v153
	v_fmac_f32_e32 v115, v150, v150
	v_fmac_f32_e32 v116, v152, v152
	v_add_f32_e32 v115, v115, v116
	v_and_b32_e32 v116, 64, v238
	v_add_f32_e32 v114, v115, v114
	v_xor_b32_e32 v115, 16, v238
	v_add_u32_e32 v117, 64, v116
	v_cmp_lt_i32_e32 vcc, v115, v117
	v_add_f32_e32 v114, v154, v114
	s_nop 0
	v_cndmask_b32_e32 v115, v238, v115, vcc
	v_lshlrev_b32_e32 v116, 2, v115
	ds_bpermute_b32 v115, v116, v114
	s_waitcnt lgkmcnt(0)
	v_add_f32_e32 v122, v114, v115
	v_xor_b32_e32 v114, 32, v238
	v_cmp_lt_i32_e32 vcc, v114, v117
	s_nop 1
	v_cndmask_b32_e32 v114, v238, v114, vcc
	v_lshlrev_b32_e32 v117, 2, v114
	ds_bpermute_b32 v123, v117, v122
	v_lshl_add_u64 v[114:115], v[224:225], 2, s[16:17]
	s_and_saveexec_b64 s[30:31], s[20:21]
	s_cbranch_execz .LBB0_778
	s_waitcnt lgkmcnt(0)
	v_add_f32_e32 v122, v122, v123
	global_atomic_add_f32 v[114:115], v122, off
.LBB0_778:
	s_or_b64 exec, exec, s[30:31]
	s_waitcnt vmcnt(16)
	v_lshlrev_b32_e32 v122, 16, v182
	s_waitcnt lgkmcnt(0)
	v_and_b32_e32 v123, 0xffff0000, v182
	v_lshlrev_b32_e32 v124, 16, v183
	v_and_b32_e32 v125, 0xffff0000, v183
	v_pk_add_f32 v[112:113], v[112:113], v[124:125]
	v_pk_add_f32 v[110:111], v[110:111], v[122:123]
	v_lshlrev_b32_e32 v122, 16, v184
	v_and_b32_e32 v123, 0xffff0000, v184
	v_lshlrev_b32_e32 v124, 16, v185
	v_and_b32_e32 v125, 0xffff0000, v185
	v_pk_add_f32 v[124:125], v[108:109], v[124:125]
	v_pk_add_f32 v[122:123], v[106:107], v[122:123]
	v_cvt_pk_bf16_f32 v106, v110, v111
	v_cvt_pk_bf16_f32 v107, v112, v113
	v_lshl_add_u64 v[150:151], s[14:15], 0, v[222:223]
	v_cvt_pk_bf16_f32 v108, v122, v123
	v_cvt_pk_bf16_f32 v109, v124, v125
	v_lshl_add_u64 v[150:151], v[208:209], 1, v[150:151]
	global_store_dwordx4 v[150:151], v[106:109], off offset:0 sc1
	s_nop 1
	v_mul_f32_e32 v106, v111, v111
	v_mul_f32_e32 v107, v113, v113
	v_fmac_f32_e32 v106, v110, v110
	v_fmac_f32_e32 v107, v112, v112
	v_add_f32_e32 v106, v106, v107
	v_mul_f32_e32 v107, v123, v123
	v_mul_f32_e32 v108, v125, v125
	v_fmac_f32_e32 v107, v122, v122
	v_fmac_f32_e32 v108, v124, v124
	v_add_f32_e32 v107, v107, v108
	v_add_f32_e32 v110, v106, v107
	s_waitcnt vmcnt(16)
	v_lshlrev_b32_e32 v106, 16, v178
	v_and_b32_e32 v107, 0xffff0000, v178
	v_lshlrev_b32_e32 v108, 16, v179
	v_and_b32_e32 v109, 0xffff0000, v179
	v_pk_add_f32 v[104:105], v[104:105], v[108:109]
	v_pk_add_f32 v[102:103], v[102:103], v[106:107]
	v_lshlrev_b32_e32 v108, 16, v181
	v_and_b32_e32 v109, 0xffff0000, v181
	v_lshlrev_b32_e32 v106, 16, v180
	v_and_b32_e32 v107, 0xffff0000, v180
	v_pk_add_f32 v[108:109], v[100:101], v[108:109]
	v_mul_f32_e32 v100, v103, v103
	v_mul_f32_e32 v101, v105, v105
	v_pk_add_f32 v[98:99], v[98:99], v[106:107]
	v_fmac_f32_e32 v100, v102, v102
	v_fmac_f32_e32 v101, v104, v104
	v_add_f32_e32 v100, v100, v101
	v_mul_f32_e32 v101, v99, v99
	v_mul_f32_e32 v106, v109, v109
	v_fmac_f32_e32 v101, v98, v98
	v_fmac_f32_e32 v106, v108, v108
	v_add_f32_e32 v101, v101, v106
	v_add_f32_e32 v100, v101, v100
	v_add_f32_e32 v106, v110, v100
	ds_bpermute_b32 v107, v116, v106
	v_cvt_pk_bf16_f32 v100, v102, v103
	v_cvt_pk_bf16_f32 v102, v98, v99
	v_cvt_pk_bf16_f32 v101, v104, v105
	v_cvt_pk_bf16_f32 v103, v108, v109
	s_waitcnt lgkmcnt(0)
	v_add_f32_e32 v98, v106, v107
	ds_bpermute_b32 v99, v117, v98
	global_store_dwordx4 v[150:151], v[100:103], off offset:0x100 sc1
	s_nop 1
	s_and_saveexec_b64 s[30:31], s[20:21]
	s_cbranch_execz .LBB0_780
	s_waitcnt lgkmcnt(0)
	v_add_f32_e32 v98, v98, v99
	global_atomic_add_f32 v[114:115], v98, off offset:64
.LBB0_780:
	s_or_b64 exec, exec, s[30:31]
	s_waitcnt vmcnt(17)
	v_lshlrev_b32_e32 v98, 16, v174
	s_waitcnt lgkmcnt(0)
	v_and_b32_e32 v99, 0xffff0000, v174
	v_lshlrev_b32_e32 v100, 16, v175
	v_and_b32_e32 v101, 0xffff0000, v175
	v_pk_add_f32 v[96:97], v[96:97], v[100:101]
	v_pk_add_f32 v[94:95], v[94:95], v[98:99]
	v_lshlrev_b32_e32 v98, 16, v176
	v_and_b32_e32 v99, 0xffff0000, v176
	v_lshlrev_b32_e32 v100, 16, v177
	v_and_b32_e32 v101, 0xffff0000, v177
	v_pk_add_f32 v[100:101], v[92:93], v[100:101]
	v_pk_add_f32 v[98:99], v[90:91], v[98:99]
	v_cvt_pk_bf16_f32 v90, v94, v95
	v_cvt_pk_bf16_f32 v91, v96, v97
	v_lshl_add_u64 v[102:103], s[14:15], 0, v[220:221]
	v_cvt_pk_bf16_f32 v92, v98, v99
	v_cvt_pk_bf16_f32 v93, v100, v101
	v_lshl_add_u64 v[102:103], v[208:209], 1, v[102:103]
	global_store_dwordx4 v[102:103], v[90:93], off offset:0 sc1
	s_nop 1
	v_mul_f32_e32 v90, v95, v95
	v_mul_f32_e32 v91, v97, v97
	v_fmac_f32_e32 v90, v94, v94
	v_fmac_f32_e32 v91, v96, v96
	v_add_f32_e32 v90, v90, v91
	v_mul_f32_e32 v91, v99, v99
	v_mul_f32_e32 v92, v101, v101
	v_fmac_f32_e32 v91, v98, v98
	v_fmac_f32_e32 v92, v100, v100
	v_add_f32_e32 v91, v91, v92
	v_add_f32_e32 v94, v90, v91
	s_waitcnt vmcnt(17)
	v_lshlrev_b32_e32 v90, 16, v170
	v_and_b32_e32 v91, 0xffff0000, v170
	v_lshlrev_b32_e32 v92, 16, v171
	v_and_b32_e32 v93, 0xffff0000, v171
	v_pk_add_f32 v[88:89], v[88:89], v[92:93]
	v_pk_add_f32 v[86:87], v[86:87], v[90:91]
	v_lshlrev_b32_e32 v92, 16, v173
	v_and_b32_e32 v93, 0xffff0000, v173
	v_lshlrev_b32_e32 v90, 16, v172
	v_and_b32_e32 v91, 0xffff0000, v172
	v_pk_add_f32 v[92:93], v[84:85], v[92:93]
	v_mul_f32_e32 v84, v87, v87
	v_mul_f32_e32 v85, v89, v89
	v_pk_add_f32 v[82:83], v[82:83], v[90:91]
	v_fmac_f32_e32 v84, v86, v86
	v_fmac_f32_e32 v85, v88, v88
	v_add_f32_e32 v84, v84, v85
	v_mul_f32_e32 v85, v83, v83
	v_mul_f32_e32 v90, v93, v93
	v_fmac_f32_e32 v85, v82, v82
	v_fmac_f32_e32 v90, v92, v92
	v_add_f32_e32 v85, v85, v90
	v_add_f32_e32 v84, v85, v84
	v_add_f32_e32 v90, v94, v84
	ds_bpermute_b32 v91, v116, v90
	v_cvt_pk_bf16_f32 v84, v86, v87
	v_cvt_pk_bf16_f32 v86, v82, v83
	v_cvt_pk_bf16_f32 v85, v88, v89
	v_cvt_pk_bf16_f32 v87, v92, v93
	s_waitcnt lgkmcnt(0)
	v_add_f32_e32 v82, v90, v91
	ds_bpermute_b32 v83, v117, v82
	global_store_dwordx4 v[102:103], v[84:87], off offset:0x100 sc1
	s_nop 1
	s_and_saveexec_b64 s[30:31], s[20:21]
	s_cbranch_execz .LBB0_782
	s_waitcnt lgkmcnt(0)
	v_add_f32_e32 v82, v82, v83
	global_atomic_add_f32 v[114:115], v82, off offset:128
.LBB0_782:
	s_or_b64 exec, exec, s[30:31]
	s_waitcnt vmcnt(18)
	v_lshlrev_b32_e32 v82, 16, v166
	s_waitcnt lgkmcnt(0)
	v_and_b32_e32 v83, 0xffff0000, v166
	v_lshlrev_b32_e32 v84, 16, v167
	v_and_b32_e32 v85, 0xffff0000, v167
	v_pk_add_f32 v[80:81], v[80:81], v[84:85]
	v_pk_add_f32 v[78:79], v[78:79], v[82:83]
	v_lshlrev_b32_e32 v82, 16, v168
	v_and_b32_e32 v83, 0xffff0000, v168
	v_lshlrev_b32_e32 v84, 16, v169
	v_and_b32_e32 v85, 0xffff0000, v169
	v_pk_add_f32 v[84:85], v[76:77], v[84:85]
	v_pk_add_f32 v[82:83], v[74:75], v[82:83]
	v_cvt_pk_bf16_f32 v74, v78, v79
	v_cvt_pk_bf16_f32 v75, v80, v81
	v_lshl_add_u64 v[86:87], s[14:15], 0, v[218:219]
	v_cvt_pk_bf16_f32 v76, v82, v83
	v_cvt_pk_bf16_f32 v77, v84, v85
	v_lshl_add_u64 v[86:87], v[208:209], 1, v[86:87]
	global_store_dwordx4 v[86:87], v[74:77], off offset:0 sc1
	s_nop 1
	v_mul_f32_e32 v74, v79, v79
	v_mul_f32_e32 v75, v81, v81
	v_fmac_f32_e32 v74, v78, v78
	v_fmac_f32_e32 v75, v80, v80
	v_add_f32_e32 v74, v74, v75
	v_mul_f32_e32 v75, v83, v83
	v_mul_f32_e32 v76, v85, v85
	v_fmac_f32_e32 v75, v82, v82
	v_fmac_f32_e32 v76, v84, v84
	v_add_f32_e32 v75, v75, v76
	v_add_f32_e32 v78, v74, v75
	s_waitcnt vmcnt(18)
	v_lshlrev_b32_e32 v74, 16, v162
	v_and_b32_e32 v75, 0xffff0000, v162
	v_lshlrev_b32_e32 v76, 16, v163
	v_and_b32_e32 v77, 0xffff0000, v163
	v_pk_add_f32 v[72:73], v[72:73], v[76:77]
	v_pk_add_f32 v[70:71], v[70:71], v[74:75]
	v_lshlrev_b32_e32 v76, 16, v165
	v_and_b32_e32 v77, 0xffff0000, v165
	v_lshlrev_b32_e32 v74, 16, v164
	v_and_b32_e32 v75, 0xffff0000, v164
	v_pk_add_f32 v[76:77], v[68:69], v[76:77]
	v_mul_f32_e32 v68, v71, v71
	v_mul_f32_e32 v69, v73, v73
	v_pk_add_f32 v[66:67], v[66:67], v[74:75]
	v_fmac_f32_e32 v68, v70, v70
	v_fmac_f32_e32 v69, v72, v72
	v_add_f32_e32 v68, v68, v69
	v_mul_f32_e32 v69, v67, v67
	v_mul_f32_e32 v74, v77, v77
	v_fmac_f32_e32 v69, v66, v66
	v_fmac_f32_e32 v74, v76, v76
	v_add_f32_e32 v69, v69, v74
	v_add_f32_e32 v68, v69, v68
	v_add_f32_e32 v74, v78, v68
	ds_bpermute_b32 v75, v116, v74
	v_cvt_pk_bf16_f32 v68, v70, v71
	v_cvt_pk_bf16_f32 v70, v66, v67
	v_cvt_pk_bf16_f32 v69, v72, v73
	v_cvt_pk_bf16_f32 v71, v76, v77
	s_waitcnt lgkmcnt(0)
	v_add_f32_e32 v66, v74, v75
	ds_bpermute_b32 v67, v117, v66
	global_store_dwordx4 v[86:87], v[68:71], off offset:0x100 sc1
	s_nop 1
	s_and_saveexec_b64 s[30:31], s[20:21]
	s_cbranch_execz .LBB0_784
	s_waitcnt lgkmcnt(0)
	v_add_f32_e32 v66, v66, v67
	global_atomic_add_f32 v[114:115], v66, off offset:192
.LBB0_784:
	s_or_b64 exec, exec, s[30:31]
	s_waitcnt vmcnt(19)
	v_lshlrev_b32_e32 v66, 16, v158
	s_waitcnt lgkmcnt(0)
	v_and_b32_e32 v67, 0xffff0000, v158
	v_lshlrev_b32_e32 v68, 16, v159
	v_and_b32_e32 v69, 0xffff0000, v159
	v_pk_add_f32 v[64:65], v[64:65], v[68:69]
	v_pk_add_f32 v[62:63], v[62:63], v[66:67]
	v_lshlrev_b32_e32 v66, 16, v160
	v_and_b32_e32 v67, 0xffff0000, v160
	v_lshlrev_b32_e32 v68, 16, v161
	v_and_b32_e32 v69, 0xffff0000, v161
	v_pk_add_f32 v[68:69], v[60:61], v[68:69]
	v_pk_add_f32 v[66:67], v[58:59], v[66:67]
	v_cvt_pk_bf16_f32 v58, v62, v63
	v_cvt_pk_bf16_f32 v59, v64, v65
	v_lshl_add_u64 v[70:71], s[14:15], 0, v[216:217]
	v_cvt_pk_bf16_f32 v60, v66, v67
	v_cvt_pk_bf16_f32 v61, v68, v69
	v_lshl_add_u64 v[70:71], v[208:209], 1, v[70:71]
	global_store_dwordx4 v[70:71], v[58:61], off offset:0 sc1
	s_nop 1
	v_mul_f32_e32 v58, v63, v63
	v_mul_f32_e32 v59, v65, v65
	v_fmac_f32_e32 v58, v62, v62
	v_fmac_f32_e32 v59, v64, v64
	v_add_f32_e32 v58, v58, v59
	v_mul_f32_e32 v59, v67, v67
	v_mul_f32_e32 v60, v69, v69
	v_fmac_f32_e32 v59, v66, v66
	v_fmac_f32_e32 v60, v68, v68
	v_add_f32_e32 v59, v59, v60
	v_add_f32_e32 v62, v58, v59
	s_waitcnt vmcnt(19)
	v_lshlrev_b32_e32 v58, 16, v146
	v_and_b32_e32 v59, 0xffff0000, v146
	v_lshlrev_b32_e32 v60, 16, v147
	v_and_b32_e32 v61, 0xffff0000, v147
	v_pk_add_f32 v[56:57], v[56:57], v[60:61]
	v_pk_add_f32 v[54:55], v[54:55], v[58:59]
	v_lshlrev_b32_e32 v60, 16, v149
	v_and_b32_e32 v61, 0xffff0000, v149
	v_lshlrev_b32_e32 v58, 16, v148
	v_and_b32_e32 v59, 0xffff0000, v148
	v_pk_add_f32 v[60:61], v[52:53], v[60:61]
	v_mul_f32_e32 v52, v55, v55
	v_mul_f32_e32 v53, v57, v57
	v_pk_add_f32 v[50:51], v[50:51], v[58:59]
	v_fmac_f32_e32 v52, v54, v54
	v_fmac_f32_e32 v53, v56, v56
	v_add_f32_e32 v52, v52, v53
	v_mul_f32_e32 v53, v51, v51
	v_mul_f32_e32 v58, v61, v61
	v_fmac_f32_e32 v53, v50, v50
	v_fmac_f32_e32 v58, v60, v60
	v_add_f32_e32 v53, v53, v58
	v_add_f32_e32 v52, v53, v52
	v_add_f32_e32 v58, v62, v52
	ds_bpermute_b32 v59, v116, v58
	v_cvt_pk_bf16_f32 v52, v54, v55
	v_cvt_pk_bf16_f32 v54, v50, v51
	v_cvt_pk_bf16_f32 v53, v56, v57
	v_cvt_pk_bf16_f32 v55, v60, v61
	s_waitcnt lgkmcnt(0)
	v_add_f32_e32 v50, v58, v59
	ds_bpermute_b32 v51, v117, v50
	global_store_dwordx4 v[70:71], v[52:55], off offset:0x100 sc1
	s_nop 1
	s_and_saveexec_b64 s[30:31], s[20:21]
	s_cbranch_execz .LBB0_786
	s_waitcnt lgkmcnt(0)
	v_add_f32_e32 v50, v50, v51
	global_atomic_add_f32 v[114:115], v50, off offset:512
.LBB0_786:
	s_or_b64 exec, exec, s[30:31]
	s_waitcnt vmcnt(20)
	v_lshlrev_b32_e32 v50, 16, v142
	s_waitcnt lgkmcnt(0)
	v_and_b32_e32 v51, 0xffff0000, v142
	v_lshlrev_b32_e32 v52, 16, v143
	v_and_b32_e32 v53, 0xffff0000, v143
	v_pk_add_f32 v[48:49], v[48:49], v[52:53]
	v_pk_add_f32 v[46:47], v[46:47], v[50:51]
	v_lshlrev_b32_e32 v50, 16, v144
	v_and_b32_e32 v51, 0xffff0000, v144
	v_lshlrev_b32_e32 v52, 16, v145
	v_and_b32_e32 v53, 0xffff0000, v145
	v_pk_add_f32 v[52:53], v[44:45], v[52:53]
	v_pk_add_f32 v[50:51], v[42:43], v[50:51]
	v_cvt_pk_bf16_f32 v42, v46, v47
	v_cvt_pk_bf16_f32 v43, v48, v49
	v_lshl_add_u64 v[54:55], s[14:15], 0, v[214:215]
	v_cvt_pk_bf16_f32 v44, v50, v51
	v_cvt_pk_bf16_f32 v45, v52, v53
	v_lshl_add_u64 v[54:55], v[208:209], 1, v[54:55]
	global_store_dwordx4 v[54:55], v[42:45], off offset:0 sc1
	s_nop 1
	v_mul_f32_e32 v42, v47, v47
	v_mul_f32_e32 v43, v49, v49
	v_fmac_f32_e32 v42, v46, v46
	v_fmac_f32_e32 v43, v48, v48
	v_add_f32_e32 v42, v42, v43
	v_mul_f32_e32 v43, v51, v51
	v_mul_f32_e32 v44, v53, v53
	v_fmac_f32_e32 v43, v50, v50
	v_fmac_f32_e32 v44, v52, v52
	v_add_f32_e32 v43, v43, v44
	v_add_f32_e32 v46, v42, v43
	s_waitcnt vmcnt(20)
	v_lshlrev_b32_e32 v42, 16, v138
	v_and_b32_e32 v43, 0xffff0000, v138
	v_lshlrev_b32_e32 v44, 16, v139
	v_and_b32_e32 v45, 0xffff0000, v139
	v_pk_add_f32 v[40:41], v[40:41], v[44:45]
	v_pk_add_f32 v[38:39], v[38:39], v[42:43]
	v_lshlrev_b32_e32 v44, 16, v141
	v_and_b32_e32 v45, 0xffff0000, v141
	v_lshlrev_b32_e32 v42, 16, v140
	v_and_b32_e32 v43, 0xffff0000, v140
	v_pk_add_f32 v[44:45], v[36:37], v[44:45]
	v_mul_f32_e32 v36, v39, v39
	v_mul_f32_e32 v37, v41, v41
	v_pk_add_f32 v[34:35], v[34:35], v[42:43]
	v_fmac_f32_e32 v36, v38, v38
	v_fmac_f32_e32 v37, v40, v40
	v_add_f32_e32 v36, v36, v37
	v_mul_f32_e32 v37, v35, v35
	v_mul_f32_e32 v42, v45, v45
	v_fmac_f32_e32 v37, v34, v34
	v_fmac_f32_e32 v42, v44, v44
	v_add_f32_e32 v37, v37, v42
	v_add_f32_e32 v36, v37, v36
	v_add_f32_e32 v42, v46, v36
	ds_bpermute_b32 v43, v116, v42
	v_cvt_pk_bf16_f32 v36, v38, v39
	v_cvt_pk_bf16_f32 v38, v34, v35
	v_cvt_pk_bf16_f32 v37, v40, v41
	v_cvt_pk_bf16_f32 v39, v44, v45
	s_waitcnt lgkmcnt(0)
	v_add_f32_e32 v34, v42, v43
	ds_bpermute_b32 v35, v117, v34
	global_store_dwordx4 v[54:55], v[36:39], off offset:0x100 sc1
	s_nop 1
	s_and_saveexec_b64 s[30:31], s[20:21]
	s_cbranch_execz .LBB0_788
	s_waitcnt lgkmcnt(0)
	v_add_f32_e32 v34, v34, v35
	global_atomic_add_f32 v[114:115], v34, off offset:576
.LBB0_788:
	s_or_b64 exec, exec, s[30:31]
	s_waitcnt vmcnt(21)
	v_lshlrev_b32_e32 v34, 16, v134
	s_waitcnt lgkmcnt(0)
	v_and_b32_e32 v35, 0xffff0000, v134
	v_lshlrev_b32_e32 v36, 16, v135
	v_and_b32_e32 v37, 0xffff0000, v135
	v_pk_add_f32 v[32:33], v[32:33], v[36:37]
	v_pk_add_f32 v[30:31], v[30:31], v[34:35]
	v_lshlrev_b32_e32 v34, 16, v136
	v_and_b32_e32 v35, 0xffff0000, v136
	v_lshlrev_b32_e32 v36, 16, v137
	v_and_b32_e32 v37, 0xffff0000, v137
	v_pk_add_f32 v[36:37], v[28:29], v[36:37]
	v_pk_add_f32 v[34:35], v[26:27], v[34:35]
	v_cvt_pk_bf16_f32 v26, v30, v31
	v_cvt_pk_bf16_f32 v27, v32, v33
	v_lshl_add_u64 v[38:39], s[14:15], 0, v[212:213]
	v_cvt_pk_bf16_f32 v28, v34, v35
	v_cvt_pk_bf16_f32 v29, v36, v37
	v_lshl_add_u64 v[38:39], v[208:209], 1, v[38:39]
	global_store_dwordx4 v[38:39], v[26:29], off offset:0 sc1
	s_nop 1
	v_mul_f32_e32 v26, v31, v31
	v_mul_f32_e32 v27, v33, v33
	v_fmac_f32_e32 v26, v30, v30
	v_fmac_f32_e32 v27, v32, v32
	v_add_f32_e32 v26, v26, v27
	v_mul_f32_e32 v27, v35, v35
	v_mul_f32_e32 v28, v37, v37
	v_fmac_f32_e32 v27, v34, v34
	v_fmac_f32_e32 v28, v36, v36
	v_add_f32_e32 v27, v27, v28
	v_add_f32_e32 v30, v26, v27
	s_waitcnt vmcnt(21)
	v_lshlrev_b32_e32 v26, 16, v126
	v_and_b32_e32 v27, 0xffff0000, v126
	v_lshlrev_b32_e32 v28, 16, v127
	v_and_b32_e32 v29, 0xffff0000, v127
	v_pk_add_f32 v[24:25], v[24:25], v[28:29]
	v_pk_add_f32 v[22:23], v[22:23], v[26:27]
	v_lshlrev_b32_e32 v28, 16, v129
	v_and_b32_e32 v29, 0xffff0000, v129
	v_lshlrev_b32_e32 v26, 16, v128
	v_and_b32_e32 v27, 0xffff0000, v128
	v_pk_add_f32 v[28:29], v[20:21], v[28:29]
	v_mul_f32_e32 v20, v23, v23
	v_mul_f32_e32 v21, v25, v25
	v_pk_add_f32 v[18:19], v[18:19], v[26:27]
	v_fmac_f32_e32 v20, v22, v22
	v_fmac_f32_e32 v21, v24, v24
	v_add_f32_e32 v20, v20, v21
	v_mul_f32_e32 v21, v19, v19
	v_mul_f32_e32 v26, v29, v29
	v_fmac_f32_e32 v21, v18, v18
	v_fmac_f32_e32 v26, v28, v28
	v_add_f32_e32 v21, v21, v26
	v_add_f32_e32 v20, v21, v20
	v_add_f32_e32 v26, v30, v20
	ds_bpermute_b32 v27, v116, v26
	v_cvt_pk_bf16_f32 v20, v22, v23
	v_cvt_pk_bf16_f32 v22, v18, v19
	v_cvt_pk_bf16_f32 v21, v24, v25
	v_cvt_pk_bf16_f32 v23, v28, v29
	s_waitcnt lgkmcnt(0)
	v_add_f32_e32 v18, v26, v27
	ds_bpermute_b32 v19, v117, v18
	global_store_dwordx4 v[38:39], v[20:23], off offset:0x100 sc1
	s_nop 1
	s_and_saveexec_b64 s[30:31], s[20:21]
	s_cbranch_execz .LBB0_790
	s_waitcnt lgkmcnt(0)
	v_add_f32_e32 v18, v18, v19
	global_atomic_add_f32 v[114:115], v18, off offset:640
.LBB0_790:
	s_or_b64 exec, exec, s[30:31]
	s_waitcnt vmcnt(22)
	v_lshlrev_b32_e32 v18, 16, v130
	s_waitcnt lgkmcnt(0)
	v_and_b32_e32 v19, 0xffff0000, v130
	v_lshlrev_b32_e32 v20, 16, v131
	v_and_b32_e32 v21, 0xffff0000, v131
	v_pk_add_f32 v[16:17], v[16:17], v[20:21]
	v_pk_add_f32 v[14:15], v[14:15], v[18:19]
	v_lshlrev_b32_e32 v18, 16, v132
	v_and_b32_e32 v19, 0xffff0000, v132
	v_lshlrev_b32_e32 v20, 16, v133
	v_and_b32_e32 v21, 0xffff0000, v133
	v_pk_add_f32 v[20:21], v[12:13], v[20:21]
	v_pk_add_f32 v[18:19], v[10:11], v[18:19]
	v_cvt_pk_bf16_f32 v10, v14, v15
	v_cvt_pk_bf16_f32 v11, v16, v17
	v_lshl_add_u64 v[22:23], s[14:15], 0, v[210:211]
	v_cvt_pk_bf16_f32 v12, v18, v19
	v_cvt_pk_bf16_f32 v13, v20, v21
	v_lshl_add_u64 v[22:23], v[208:209], 1, v[22:23]
	global_store_dwordx4 v[22:23], v[10:13], off offset:0 sc1
	s_nop 1
	v_mul_f32_e32 v10, v15, v15
	v_mul_f32_e32 v11, v17, v17
	v_fmac_f32_e32 v10, v14, v14
	v_fmac_f32_e32 v11, v16, v16
	v_add_f32_e32 v10, v10, v11
	v_mul_f32_e32 v11, v19, v19
	v_mul_f32_e32 v12, v21, v21
	v_fmac_f32_e32 v11, v18, v18
	v_fmac_f32_e32 v12, v20, v20
	v_add_f32_e32 v11, v11, v12
	v_add_f32_e32 v14, v10, v11
	s_waitcnt vmcnt(22)
	v_lshlrev_b32_e32 v10, 16, v118
	v_and_b32_e32 v11, 0xffff0000, v118
	v_lshlrev_b32_e32 v12, 16, v119
	v_and_b32_e32 v13, 0xffff0000, v119
	v_pk_add_f32 v[8:9], v[8:9], v[12:13]
	v_pk_add_f32 v[6:7], v[6:7], v[10:11]
	v_lshlrev_b32_e32 v12, 16, v121
	v_and_b32_e32 v13, 0xffff0000, v121
	v_lshlrev_b32_e32 v10, 16, v120
	v_and_b32_e32 v11, 0xffff0000, v120
	v_pk_add_f32 v[12:13], v[4:5], v[12:13]
	v_mul_f32_e32 v4, v7, v7
	v_mul_f32_e32 v5, v9, v9
	v_pk_add_f32 v[2:3], v[2:3], v[10:11]
	v_fmac_f32_e32 v4, v6, v6
	v_fmac_f32_e32 v5, v8, v8
	v_add_f32_e32 v4, v4, v5
	v_mul_f32_e32 v5, v3, v3
	v_mul_f32_e32 v10, v13, v13
	v_fmac_f32_e32 v5, v2, v2
	v_fmac_f32_e32 v10, v12, v12
	v_add_f32_e32 v5, v5, v10
	v_add_f32_e32 v4, v5, v4
	v_add_f32_e32 v10, v14, v4
	ds_bpermute_b32 v11, v116, v10
	v_cvt_pk_bf16_f32 v4, v6, v7
	v_cvt_pk_bf16_f32 v6, v2, v3
	v_cvt_pk_bf16_f32 v5, v8, v9
	v_cvt_pk_bf16_f32 v7, v12, v13
	s_waitcnt lgkmcnt(0)
	v_add_f32_e32 v2, v10, v11
	ds_bpermute_b32 v3, v117, v2
	global_store_dwordx4 v[22:23], v[4:7], off offset:0x100 sc1
	s_nop 1
	s_and_saveexec_b64 s[30:31], s[20:21]
	s_cbranch_execz .LBB0_792
	s_waitcnt lgkmcnt(0)
	v_add_f32_e32 v2, v2, v3
	global_atomic_add_f32 v[114:115], v2, off offset:704

.LBB0_918:
	v_lshl_or_b32 v208, s70, 8, v241
	v_lshl_add_u32 v224, s71, 8, v230
	v_ashrrev_i32_e32 v209, 31, v208
	v_lshlrev_b64 v[226:227], 1, v[208:209]
	v_ashrrev_i32_e32 v225, 31, v224
	v_lshl_add_u64 v[118:119], s[16:17], 0, v[226:227]
	v_lshlrev_b64 v[228:229], 11, v[224:225]
	v_lshl_add_u64 v[120:121], v[118:119], 0, v[228:229]
	global_load_dwordx4 v[234:237], v[120:121], off
	global_load_dwordx4 v[186:189], v[120:121], off offset:256
	v_or_b32_e32 v120, 16, v224
	v_ashrrev_i32_e32 v121, 31, v120
	v_lshlrev_b64 v[222:223], 11, v[120:121]
	v_lshl_add_u64 v[120:121], v[118:119], 0, v[222:223]
	global_load_dwordx4 v[182:185], v[120:121], off
	global_load_dwordx4 v[178:181], v[120:121], off offset:256
	v_or_b32_e32 v120, 32, v224
	v_ashrrev_i32_e32 v121, 31, v120
	v_lshlrev_b64 v[220:221], 11, v[120:121]
	v_lshl_add_u64 v[120:121], v[118:119], 0, v[220:221]
	global_load_dwordx4 v[174:177], v[120:121], off
	global_load_dwordx4 v[170:173], v[120:121], off offset:256
	v_or_b32_e32 v120, 48, v224
	v_ashrrev_i32_e32 v121, 31, v120
	v_lshlrev_b64 v[218:219], 11, v[120:121]
	v_lshl_add_u64 v[120:121], v[118:119], 0, v[218:219]
	v_lshl_add_u64 v[216:217], v[228:229], 0, s[88:89]
	global_load_dwordx4 v[166:169], v[120:121], off
	global_load_dwordx4 v[162:165], v[120:121], off offset:256
	v_lshl_add_u64 v[120:121], v[118:119], 0, v[216:217]
	v_lshl_add_u64 v[214:215], v[228:229], 0, s[60:61]
	global_load_dwordx4 v[158:161], v[120:121], off
	global_load_dwordx4 v[146:149], v[120:121], off offset:256
	v_lshl_add_u64 v[120:121], v[118:119], 0, v[214:215]
	v_lshl_add_u64 v[212:213], v[228:229], 0, s[62:63]
	v_lshl_add_u64 v[210:211], v[228:229], 0, s[66:67]
	global_load_dwordx4 v[142:145], v[120:121], off
	global_load_dwordx4 v[138:141], v[120:121], off offset:256
	v_lshl_add_u64 v[120:121], v[118:119], 0, v[212:213]
	v_lshl_add_u64 v[118:119], v[118:119], 0, v[210:211]
	global_load_dwordx4 v[134:137], v[120:121], off
	global_load_dwordx4 v[126:129], v[120:121], off offset:256
	global_load_dwordx4 v[130:133], v[118:119], off
	s_nop 0
	global_load_dwordx4 v[118:121], v[118:119], off offset:256
	v_lshl_add_u64 v[228:229], s[16:17], 0, v[228:229]
	v_lshl_add_u64 v[226:227], v[228:229], 0, v[226:227]
	s_waitcnt vmcnt(15)
	v_lshlrev_b32_e32 v194, 16, v234
	v_and_b32_e32 v195, 0xffff0000, v234
	v_lshlrev_b32_e32 v198, 16, v235
	v_and_b32_e32 v199, 0xffff0000, v235
	v_pk_add_f32 v[156:157], v[156:157], v[198:199]
	v_pk_add_f32 v[154:155], v[154:155], v[194:195]
	v_lshlrev_b32_e32 v194, 16, v236
	v_and_b32_e32 v195, 0xffff0000, v236
	v_lshlrev_b32_e32 v198, 16, v237
	v_and_b32_e32 v199, 0xffff0000, v237
	v_pk_add_f32 v[198:199], v[152:153], v[198:199]
	v_pk_add_f32 v[194:195], v[150:151], v[194:195]
	v_cvt_pk_bf16_f32 v150, v154, v155
	v_cvt_pk_bf16_f32 v151, v156, v157
	v_cvt_pk_bf16_f32 v152, v194, v195
	v_cvt_pk_bf16_f32 v153, v198, v199
	global_store_dwordx4 v[226:227], v[150:153], off offset:0 sc1
	s_nop 1
	v_mul_f32_e32 v150, v155, v155
	v_mul_f32_e32 v151, v157, v157
	v_fmac_f32_e32 v150, v154, v154
	v_fmac_f32_e32 v151, v156, v156
	v_add_f32_e32 v150, v150, v151
	v_mul_f32_e32 v151, v195, v195
	v_mul_f32_e32 v152, v199, v199
	v_fmac_f32_e32 v151, v194, v194
	v_fmac_f32_e32 v152, v198, v198
	v_add_f32_e32 v151, v151, v152
	v_add_f32_e32 v154, v150, v151
	s_waitcnt vmcnt(15)
	v_lshlrev_b32_e32 v150, 16, v186
	v_and_b32_e32 v151, 0xffff0000, v186
	v_lshlrev_b32_e32 v152, 16, v187
	v_and_b32_e32 v153, 0xffff0000, v187
	v_pk_add_f32 v[124:125], v[124:125], v[152:153]
	v_pk_add_f32 v[122:123], v[122:123], v[150:151]
	v_lshlrev_b32_e32 v150, 16, v188
	v_and_b32_e32 v151, 0xffff0000, v188
	v_lshlrev_b32_e32 v152, 16, v189
	v_and_b32_e32 v153, 0xffff0000, v189
	v_pk_add_f32 v[152:153], v[116:117], v[152:153]
	v_pk_add_f32 v[150:151], v[114:115], v[150:151]
	v_cvt_pk_bf16_f32 v114, v122, v123
	v_cvt_pk_bf16_f32 v115, v124, v125
	v_cvt_pk_bf16_f32 v116, v150, v151
	v_cvt_pk_bf16_f32 v117, v152, v153
	global_store_dwordx4 v[226:227], v[114:117], off offset:0x100 sc1
	s_nop 1
	v_mul_f32_e32 v114, v123, v123
	v_mul_f32_e32 v115, v125, v125
	v_fmac_f32_e32 v114, v122, v122
	v_fmac_f32_e32 v115, v124, v124
	v_add_f32_e32 v114, v114, v115
	v_mul_f32_e32 v115, v151, v151
	v_mul_f32_e32 v116, v153, v153
	v_fmac_f32_e32 v115, v150, v150
	v_fmac_f32_e32 v116, v152, v152
	v_add_f32_e32 v115, v115, v116
	v_and_b32_e32 v116, 64, v238
	v_add_f32_e32 v114, v115, v114
	v_xor_b32_e32 v115, 16, v238
	v_add_u32_e32 v117, 64, v116
	v_cmp_lt_i32_e32 vcc, v115, v117
	v_add_f32_e32 v114, v154, v114
	s_nop 0
	v_cndmask_b32_e32 v115, v238, v115, vcc
	v_lshlrev_b32_e32 v116, 2, v115
	ds_bpermute_b32 v115, v116, v114
	s_waitcnt lgkmcnt(0)
	v_add_f32_e32 v122, v114, v115
	v_xor_b32_e32 v114, 32, v238
	v_cmp_lt_i32_e32 vcc, v114, v117
	s_nop 1
	v_cndmask_b32_e32 v114, v238, v114, vcc
	v_lshlrev_b32_e32 v117, 2, v114
	ds_bpermute_b32 v123, v117, v122
	v_lshl_add_u64 v[114:115], v[224:225], 2, s[18:19]
	s_and_saveexec_b64 s[34:35], s[22:23]
	s_cbranch_execz .LBB0_920
	s_waitcnt lgkmcnt(0)
	v_add_f32_e32 v122, v122, v123
	global_atomic_add_f32 v[114:115], v122, off
.LBB0_920:
	s_or_b64 exec, exec, s[34:35]
	s_waitcnt vmcnt(16)
	v_lshlrev_b32_e32 v122, 16, v182
	s_waitcnt lgkmcnt(0)
	v_and_b32_e32 v123, 0xffff0000, v182
	v_lshlrev_b32_e32 v124, 16, v183
	v_and_b32_e32 v125, 0xffff0000, v183
	v_pk_add_f32 v[112:113], v[112:113], v[124:125]
	v_pk_add_f32 v[110:111], v[110:111], v[122:123]
	v_lshlrev_b32_e32 v122, 16, v184
	v_and_b32_e32 v123, 0xffff0000, v184
	v_lshlrev_b32_e32 v124, 16, v185
	v_and_b32_e32 v125, 0xffff0000, v185
	v_pk_add_f32 v[124:125], v[108:109], v[124:125]
	v_pk_add_f32 v[122:123], v[106:107], v[122:123]
	v_cvt_pk_bf16_f32 v106, v110, v111
	v_cvt_pk_bf16_f32 v107, v112, v113
	v_lshl_add_u64 v[150:151], s[16:17], 0, v[222:223]
	v_cvt_pk_bf16_f32 v108, v122, v123
	v_cvt_pk_bf16_f32 v109, v124, v125
	v_lshl_add_u64 v[150:151], v[208:209], 1, v[150:151]
	global_store_dwordx4 v[150:151], v[106:109], off offset:0 sc1
	s_nop 1
	v_mul_f32_e32 v106, v111, v111
	v_mul_f32_e32 v107, v113, v113
	v_fmac_f32_e32 v106, v110, v110
	v_fmac_f32_e32 v107, v112, v112
	v_add_f32_e32 v106, v106, v107
	v_mul_f32_e32 v107, v123, v123
	v_mul_f32_e32 v108, v125, v125
	v_fmac_f32_e32 v107, v122, v122
	v_fmac_f32_e32 v108, v124, v124
	v_add_f32_e32 v107, v107, v108
	v_add_f32_e32 v110, v106, v107
	s_waitcnt vmcnt(16)
	v_lshlrev_b32_e32 v106, 16, v178
	v_and_b32_e32 v107, 0xffff0000, v178
	v_lshlrev_b32_e32 v108, 16, v179
	v_and_b32_e32 v109, 0xffff0000, v179
	v_pk_add_f32 v[104:105], v[104:105], v[108:109]
	v_pk_add_f32 v[102:103], v[102:103], v[106:107]
	v_lshlrev_b32_e32 v108, 16, v181
	v_and_b32_e32 v109, 0xffff0000, v181
	v_lshlrev_b32_e32 v106, 16, v180
	v_and_b32_e32 v107, 0xffff0000, v180
	v_pk_add_f32 v[108:109], v[100:101], v[108:109]
	v_mul_f32_e32 v100, v103, v103
	v_mul_f32_e32 v101, v105, v105
	v_pk_add_f32 v[98:99], v[98:99], v[106:107]
	v_fmac_f32_e32 v100, v102, v102
	v_fmac_f32_e32 v101, v104, v104
	v_add_f32_e32 v100, v100, v101
	v_mul_f32_e32 v101, v99, v99
	v_mul_f32_e32 v106, v109, v109
	v_fmac_f32_e32 v101, v98, v98
	v_fmac_f32_e32 v106, v108, v108
	v_add_f32_e32 v101, v101, v106
	v_add_f32_e32 v100, v101, v100
	v_add_f32_e32 v106, v110, v100
	ds_bpermute_b32 v107, v116, v106
	v_cvt_pk_bf16_f32 v100, v102, v103
	v_cvt_pk_bf16_f32 v102, v98, v99
	v_cvt_pk_bf16_f32 v101, v104, v105
	v_cvt_pk_bf16_f32 v103, v108, v109
	s_waitcnt lgkmcnt(0)
	v_add_f32_e32 v98, v106, v107
	ds_bpermute_b32 v99, v117, v98
	global_store_dwordx4 v[150:151], v[100:103], off offset:0x100 sc1
	s_nop 1
	s_and_saveexec_b64 s[34:35], s[22:23]
	s_cbranch_execz .LBB0_922
	s_waitcnt lgkmcnt(0)
	v_add_f32_e32 v98, v98, v99
	global_atomic_add_f32 v[114:115], v98, off offset:64
.LBB0_922:
	s_or_b64 exec, exec, s[34:35]
	s_waitcnt vmcnt(17)
	v_lshlrev_b32_e32 v98, 16, v174
	s_waitcnt lgkmcnt(0)
	v_and_b32_e32 v99, 0xffff0000, v174
	v_lshlrev_b32_e32 v100, 16, v175
	v_and_b32_e32 v101, 0xffff0000, v175
	v_pk_add_f32 v[96:97], v[96:97], v[100:101]
	v_pk_add_f32 v[94:95], v[94:95], v[98:99]
	v_lshlrev_b32_e32 v98, 16, v176
	v_and_b32_e32 v99, 0xffff0000, v176
	v_lshlrev_b32_e32 v100, 16, v177
	v_and_b32_e32 v101, 0xffff0000, v177
	v_pk_add_f32 v[100:101], v[92:93], v[100:101]
	v_pk_add_f32 v[98:99], v[90:91], v[98:99]
	v_cvt_pk_bf16_f32 v90, v94, v95
	v_cvt_pk_bf16_f32 v91, v96, v97
	v_lshl_add_u64 v[102:103], s[16:17], 0, v[220:221]
	v_cvt_pk_bf16_f32 v92, v98, v99
	v_cvt_pk_bf16_f32 v93, v100, v101
	v_lshl_add_u64 v[102:103], v[208:209], 1, v[102:103]
	global_store_dwordx4 v[102:103], v[90:93], off offset:0 sc1
	s_nop 1
	v_mul_f32_e32 v90, v95, v95
	v_mul_f32_e32 v91, v97, v97
	v_fmac_f32_e32 v90, v94, v94
	v_fmac_f32_e32 v91, v96, v96
	v_add_f32_e32 v90, v90, v91
	v_mul_f32_e32 v91, v99, v99
	v_mul_f32_e32 v92, v101, v101
	v_fmac_f32_e32 v91, v98, v98
	v_fmac_f32_e32 v92, v100, v100
	v_add_f32_e32 v91, v91, v92
	v_add_f32_e32 v94, v90, v91
	s_waitcnt vmcnt(17)
	v_lshlrev_b32_e32 v90, 16, v170
	v_and_b32_e32 v91, 0xffff0000, v170
	v_lshlrev_b32_e32 v92, 16, v171
	v_and_b32_e32 v93, 0xffff0000, v171
	v_pk_add_f32 v[88:89], v[88:89], v[92:93]
	v_pk_add_f32 v[86:87], v[86:87], v[90:91]
	v_lshlrev_b32_e32 v92, 16, v173
	v_and_b32_e32 v93, 0xffff0000, v173
	v_lshlrev_b32_e32 v90, 16, v172
	v_and_b32_e32 v91, 0xffff0000, v172
	v_pk_add_f32 v[92:93], v[84:85], v[92:93]
	v_mul_f32_e32 v84, v87, v87
	v_mul_f32_e32 v85, v89, v89
	v_pk_add_f32 v[82:83], v[82:83], v[90:91]
	v_fmac_f32_e32 v84, v86, v86
	v_fmac_f32_e32 v85, v88, v88
	v_add_f32_e32 v84, v84, v85
	v_mul_f32_e32 v85, v83, v83
	v_mul_f32_e32 v90, v93, v93
	v_fmac_f32_e32 v85, v82, v82
	v_fmac_f32_e32 v90, v92, v92
	v_add_f32_e32 v85, v85, v90
	v_add_f32_e32 v84, v85, v84
	v_add_f32_e32 v90, v94, v84
	ds_bpermute_b32 v91, v116, v90
	v_cvt_pk_bf16_f32 v84, v86, v87
	v_cvt_pk_bf16_f32 v86, v82, v83
	v_cvt_pk_bf16_f32 v85, v88, v89
	v_cvt_pk_bf16_f32 v87, v92, v93
	s_waitcnt lgkmcnt(0)
	v_add_f32_e32 v82, v90, v91
	ds_bpermute_b32 v83, v117, v82
	global_store_dwordx4 v[102:103], v[84:87], off offset:0x100 sc1
	s_nop 1
	s_and_saveexec_b64 s[34:35], s[22:23]
	s_cbranch_execz .LBB0_924
	s_waitcnt lgkmcnt(0)
	v_add_f32_e32 v82, v82, v83
	global_atomic_add_f32 v[114:115], v82, off offset:128
.LBB0_924:
	s_or_b64 exec, exec, s[34:35]
	s_waitcnt vmcnt(18)
	v_lshlrev_b32_e32 v82, 16, v166
	s_waitcnt lgkmcnt(0)
	v_and_b32_e32 v83, 0xffff0000, v166
	v_lshlrev_b32_e32 v84, 16, v167
	v_and_b32_e32 v85, 0xffff0000, v167
	v_pk_add_f32 v[80:81], v[80:81], v[84:85]
	v_pk_add_f32 v[78:79], v[78:79], v[82:83]
	v_lshlrev_b32_e32 v82, 16, v168
	v_and_b32_e32 v83, 0xffff0000, v168
	v_lshlrev_b32_e32 v84, 16, v169
	v_and_b32_e32 v85, 0xffff0000, v169
	v_pk_add_f32 v[84:85], v[76:77], v[84:85]
	v_pk_add_f32 v[82:83], v[74:75], v[82:83]
	v_cvt_pk_bf16_f32 v74, v78, v79
	v_cvt_pk_bf16_f32 v75, v80, v81
	v_lshl_add_u64 v[86:87], s[16:17], 0, v[218:219]
	v_cvt_pk_bf16_f32 v76, v82, v83
	v_cvt_pk_bf16_f32 v77, v84, v85
	v_lshl_add_u64 v[86:87], v[208:209], 1, v[86:87]
	global_store_dwordx4 v[86:87], v[74:77], off offset:0 sc1
	s_nop 1
	v_mul_f32_e32 v74, v79, v79
	v_mul_f32_e32 v75, v81, v81
	v_fmac_f32_e32 v74, v78, v78
	v_fmac_f32_e32 v75, v80, v80
	v_add_f32_e32 v74, v74, v75
	v_mul_f32_e32 v75, v83, v83
	v_mul_f32_e32 v76, v85, v85
	v_fmac_f32_e32 v75, v82, v82
	v_fmac_f32_e32 v76, v84, v84
	v_add_f32_e32 v75, v75, v76
	v_add_f32_e32 v78, v74, v75
	s_waitcnt vmcnt(18)
	v_lshlrev_b32_e32 v74, 16, v162
	v_and_b32_e32 v75, 0xffff0000, v162
	v_lshlrev_b32_e32 v76, 16, v163
	v_and_b32_e32 v77, 0xffff0000, v163
	v_pk_add_f32 v[72:73], v[72:73], v[76:77]
	v_pk_add_f32 v[70:71], v[70:71], v[74:75]
	v_lshlrev_b32_e32 v76, 16, v165
	v_and_b32_e32 v77, 0xffff0000, v165
	v_lshlrev_b32_e32 v74, 16, v164
	v_and_b32_e32 v75, 0xffff0000, v164
	v_pk_add_f32 v[76:77], v[68:69], v[76:77]
	v_mul_f32_e32 v68, v71, v71
	v_mul_f32_e32 v69, v73, v73
	v_pk_add_f32 v[66:67], v[66:67], v[74:75]
	v_fmac_f32_e32 v68, v70, v70
	v_fmac_f32_e32 v69, v72, v72
	v_add_f32_e32 v68, v68, v69
	v_mul_f32_e32 v69, v67, v67
	v_mul_f32_e32 v74, v77, v77
	v_fmac_f32_e32 v69, v66, v66
	v_fmac_f32_e32 v74, v76, v76
	v_add_f32_e32 v69, v69, v74
	v_add_f32_e32 v68, v69, v68
	v_add_f32_e32 v74, v78, v68
	ds_bpermute_b32 v75, v116, v74
	v_cvt_pk_bf16_f32 v68, v70, v71
	v_cvt_pk_bf16_f32 v70, v66, v67
	v_cvt_pk_bf16_f32 v69, v72, v73
	v_cvt_pk_bf16_f32 v71, v76, v77
	s_waitcnt lgkmcnt(0)
	v_add_f32_e32 v66, v74, v75
	ds_bpermute_b32 v67, v117, v66
	global_store_dwordx4 v[86:87], v[68:71], off offset:0x100 sc1
	s_nop 1
	s_and_saveexec_b64 s[34:35], s[22:23]
	s_cbranch_execz .LBB0_926
	s_waitcnt lgkmcnt(0)
	v_add_f32_e32 v66, v66, v67
	global_atomic_add_f32 v[114:115], v66, off offset:192
.LBB0_926:
	s_or_b64 exec, exec, s[34:35]
	s_waitcnt vmcnt(19)
	v_lshlrev_b32_e32 v66, 16, v158
	s_waitcnt lgkmcnt(0)
	v_and_b32_e32 v67, 0xffff0000, v158
	v_lshlrev_b32_e32 v68, 16, v159
	v_and_b32_e32 v69, 0xffff0000, v159
	v_pk_add_f32 v[64:65], v[64:65], v[68:69]
	v_pk_add_f32 v[62:63], v[62:63], v[66:67]
	v_lshlrev_b32_e32 v66, 16, v160
	v_and_b32_e32 v67, 0xffff0000, v160
	v_lshlrev_b32_e32 v68, 16, v161
	v_and_b32_e32 v69, 0xffff0000, v161
	v_pk_add_f32 v[68:69], v[60:61], v[68:69]
	v_pk_add_f32 v[66:67], v[58:59], v[66:67]
	v_cvt_pk_bf16_f32 v58, v62, v63
	v_cvt_pk_bf16_f32 v59, v64, v65
	v_lshl_add_u64 v[70:71], s[16:17], 0, v[216:217]
	v_cvt_pk_bf16_f32 v60, v66, v67
	v_cvt_pk_bf16_f32 v61, v68, v69
	v_lshl_add_u64 v[70:71], v[208:209], 1, v[70:71]
	global_store_dwordx4 v[70:71], v[58:61], off offset:0 sc1
	s_nop 1
	v_mul_f32_e32 v58, v63, v63
	v_mul_f32_e32 v59, v65, v65
	v_fmac_f32_e32 v58, v62, v62
	v_fmac_f32_e32 v59, v64, v64
	v_add_f32_e32 v58, v58, v59
	v_mul_f32_e32 v59, v67, v67
	v_mul_f32_e32 v60, v69, v69
	v_fmac_f32_e32 v59, v66, v66
	v_fmac_f32_e32 v60, v68, v68
	v_add_f32_e32 v59, v59, v60
	v_add_f32_e32 v62, v58, v59
	s_waitcnt vmcnt(19)
	v_lshlrev_b32_e32 v58, 16, v146
	v_and_b32_e32 v59, 0xffff0000, v146
	v_lshlrev_b32_e32 v60, 16, v147
	v_and_b32_e32 v61, 0xffff0000, v147
	v_pk_add_f32 v[56:57], v[56:57], v[60:61]
	v_pk_add_f32 v[54:55], v[54:55], v[58:59]
	v_lshlrev_b32_e32 v60, 16, v149
	v_and_b32_e32 v61, 0xffff0000, v149
	v_lshlrev_b32_e32 v58, 16, v148
	v_and_b32_e32 v59, 0xffff0000, v148
	v_pk_add_f32 v[60:61], v[52:53], v[60:61]
	v_mul_f32_e32 v52, v55, v55
	v_mul_f32_e32 v53, v57, v57
	v_pk_add_f32 v[50:51], v[50:51], v[58:59]
	v_fmac_f32_e32 v52, v54, v54
	v_fmac_f32_e32 v53, v56, v56
	v_add_f32_e32 v52, v52, v53
	v_mul_f32_e32 v53, v51, v51
	v_mul_f32_e32 v58, v61, v61
	v_fmac_f32_e32 v53, v50, v50
	v_fmac_f32_e32 v58, v60, v60
	v_add_f32_e32 v53, v53, v58
	v_add_f32_e32 v52, v53, v52
	v_add_f32_e32 v58, v62, v52
	ds_bpermute_b32 v59, v116, v58
	v_cvt_pk_bf16_f32 v52, v54, v55
	v_cvt_pk_bf16_f32 v54, v50, v51
	v_cvt_pk_bf16_f32 v53, v56, v57
	v_cvt_pk_bf16_f32 v55, v60, v61
	s_waitcnt lgkmcnt(0)
	v_add_f32_e32 v50, v58, v59
	ds_bpermute_b32 v51, v117, v50
	global_store_dwordx4 v[70:71], v[52:55], off offset:0x100 sc1
	s_nop 1
	s_and_saveexec_b64 s[34:35], s[22:23]
	s_cbranch_execz .LBB0_928
	s_waitcnt lgkmcnt(0)
	v_add_f32_e32 v50, v50, v51
	global_atomic_add_f32 v[114:115], v50, off offset:512
.LBB0_928:
	s_or_b64 exec, exec, s[34:35]
	s_waitcnt vmcnt(20)
	v_lshlrev_b32_e32 v50, 16, v142
	s_waitcnt lgkmcnt(0)
	v_and_b32_e32 v51, 0xffff0000, v142
	v_lshlrev_b32_e32 v52, 16, v143
	v_and_b32_e32 v53, 0xffff0000, v143
	v_pk_add_f32 v[48:49], v[48:49], v[52:53]
	v_pk_add_f32 v[46:47], v[46:47], v[50:51]
	v_lshlrev_b32_e32 v50, 16, v144
	v_and_b32_e32 v51, 0xffff0000, v144
	v_lshlrev_b32_e32 v52, 16, v145
	v_and_b32_e32 v53, 0xffff0000, v145
	v_pk_add_f32 v[52:53], v[44:45], v[52:53]
	v_pk_add_f32 v[50:51], v[42:43], v[50:51]
	v_cvt_pk_bf16_f32 v42, v46, v47
	v_cvt_pk_bf16_f32 v43, v48, v49
	v_lshl_add_u64 v[54:55], s[16:17], 0, v[214:215]
	v_cvt_pk_bf16_f32 v44, v50, v51
	v_cvt_pk_bf16_f32 v45, v52, v53
	v_lshl_add_u64 v[54:55], v[208:209], 1, v[54:55]
	global_store_dwordx4 v[54:55], v[42:45], off offset:0 sc1
	s_nop 1
	v_mul_f32_e32 v42, v47, v47
	v_mul_f32_e32 v43, v49, v49
	v_fmac_f32_e32 v42, v46, v46
	v_fmac_f32_e32 v43, v48, v48
	v_add_f32_e32 v42, v42, v43
	v_mul_f32_e32 v43, v51, v51
	v_mul_f32_e32 v44, v53, v53
	v_fmac_f32_e32 v43, v50, v50
	v_fmac_f32_e32 v44, v52, v52
	v_add_f32_e32 v43, v43, v44
	v_add_f32_e32 v46, v42, v43
	s_waitcnt vmcnt(20)
	v_lshlrev_b32_e32 v42, 16, v138
	v_and_b32_e32 v43, 0xffff0000, v138
	v_lshlrev_b32_e32 v44, 16, v139
	v_and_b32_e32 v45, 0xffff0000, v139
	v_pk_add_f32 v[40:41], v[40:41], v[44:45]
	v_pk_add_f32 v[38:39], v[38:39], v[42:43]
	v_lshlrev_b32_e32 v44, 16, v141
	v_and_b32_e32 v45, 0xffff0000, v141
	v_lshlrev_b32_e32 v42, 16, v140
	v_and_b32_e32 v43, 0xffff0000, v140
	v_pk_add_f32 v[44:45], v[36:37], v[44:45]
	v_mul_f32_e32 v36, v39, v39
	v_mul_f32_e32 v37, v41, v41
	v_pk_add_f32 v[34:35], v[34:35], v[42:43]
	v_fmac_f32_e32 v36, v38, v38
	v_fmac_f32_e32 v37, v40, v40
	v_add_f32_e32 v36, v36, v37
	v_mul_f32_e32 v37, v35, v35
	v_mul_f32_e32 v42, v45, v45
	v_fmac_f32_e32 v37, v34, v34
	v_fmac_f32_e32 v42, v44, v44
	v_add_f32_e32 v37, v37, v42
	v_add_f32_e32 v36, v37, v36
	v_add_f32_e32 v42, v46, v36
	ds_bpermute_b32 v43, v116, v42
	v_cvt_pk_bf16_f32 v36, v38, v39
	v_cvt_pk_bf16_f32 v38, v34, v35
	v_cvt_pk_bf16_f32 v37, v40, v41
	v_cvt_pk_bf16_f32 v39, v44, v45
	s_waitcnt lgkmcnt(0)
	v_add_f32_e32 v34, v42, v43
	ds_bpermute_b32 v35, v117, v34
	global_store_dwordx4 v[54:55], v[36:39], off offset:0x100 sc1
	s_nop 1
	s_and_saveexec_b64 s[34:35], s[22:23]
	s_cbranch_execz .LBB0_930
	s_waitcnt lgkmcnt(0)
	v_add_f32_e32 v34, v34, v35
	global_atomic_add_f32 v[114:115], v34, off offset:576
.LBB0_930:
	s_or_b64 exec, exec, s[34:35]
	s_waitcnt vmcnt(21)
	v_lshlrev_b32_e32 v34, 16, v134
	s_waitcnt lgkmcnt(0)
	v_and_b32_e32 v35, 0xffff0000, v134
	v_lshlrev_b32_e32 v36, 16, v135
	v_and_b32_e32 v37, 0xffff0000, v135
	v_pk_add_f32 v[32:33], v[32:33], v[36:37]
	v_pk_add_f32 v[30:31], v[30:31], v[34:35]
	v_lshlrev_b32_e32 v34, 16, v136
	v_and_b32_e32 v35, 0xffff0000, v136
	v_lshlrev_b32_e32 v36, 16, v137
	v_and_b32_e32 v37, 0xffff0000, v137
	v_pk_add_f32 v[36:37], v[28:29], v[36:37]
	v_pk_add_f32 v[34:35], v[26:27], v[34:35]
	v_cvt_pk_bf16_f32 v26, v30, v31
	v_cvt_pk_bf16_f32 v27, v32, v33
	v_lshl_add_u64 v[38:39], s[16:17], 0, v[212:213]
	v_cvt_pk_bf16_f32 v28, v34, v35
	v_cvt_pk_bf16_f32 v29, v36, v37
	v_lshl_add_u64 v[38:39], v[208:209], 1, v[38:39]
	global_store_dwordx4 v[38:39], v[26:29], off offset:0 sc1
	s_nop 1
	v_mul_f32_e32 v26, v31, v31
	v_mul_f32_e32 v27, v33, v33
	v_fmac_f32_e32 v26, v30, v30
	v_fmac_f32_e32 v27, v32, v32
	v_add_f32_e32 v26, v26, v27
	v_mul_f32_e32 v27, v35, v35
	v_mul_f32_e32 v28, v37, v37
	v_fmac_f32_e32 v27, v34, v34
	v_fmac_f32_e32 v28, v36, v36
	v_add_f32_e32 v27, v27, v28
	v_add_f32_e32 v30, v26, v27
	s_waitcnt vmcnt(21)
	v_lshlrev_b32_e32 v26, 16, v126
	v_and_b32_e32 v27, 0xffff0000, v126
	v_lshlrev_b32_e32 v28, 16, v127
	v_and_b32_e32 v29, 0xffff0000, v127
	v_pk_add_f32 v[24:25], v[24:25], v[28:29]
	v_pk_add_f32 v[22:23], v[22:23], v[26:27]
	v_lshlrev_b32_e32 v28, 16, v129
	v_and_b32_e32 v29, 0xffff0000, v129
	v_lshlrev_b32_e32 v26, 16, v128
	v_and_b32_e32 v27, 0xffff0000, v128
	v_pk_add_f32 v[28:29], v[20:21], v[28:29]
	v_mul_f32_e32 v20, v23, v23
	v_mul_f32_e32 v21, v25, v25
	v_pk_add_f32 v[18:19], v[18:19], v[26:27]
	v_fmac_f32_e32 v20, v22, v22
	v_fmac_f32_e32 v21, v24, v24
	v_add_f32_e32 v20, v20, v21
	v_mul_f32_e32 v21, v19, v19
	v_mul_f32_e32 v26, v29, v29
	v_fmac_f32_e32 v21, v18, v18
	v_fmac_f32_e32 v26, v28, v28
	v_add_f32_e32 v21, v21, v26
	v_add_f32_e32 v20, v21, v20
	v_add_f32_e32 v26, v30, v20
	ds_bpermute_b32 v27, v116, v26
	v_cvt_pk_bf16_f32 v20, v22, v23
	v_cvt_pk_bf16_f32 v22, v18, v19
	v_cvt_pk_bf16_f32 v21, v24, v25
	v_cvt_pk_bf16_f32 v23, v28, v29
	s_waitcnt lgkmcnt(0)
	v_add_f32_e32 v18, v26, v27
	ds_bpermute_b32 v19, v117, v18
	global_store_dwordx4 v[38:39], v[20:23], off offset:0x100 sc1
	s_nop 1
	s_and_saveexec_b64 s[34:35], s[22:23]
	s_cbranch_execz .LBB0_932
	s_waitcnt lgkmcnt(0)
	v_add_f32_e32 v18, v18, v19
	global_atomic_add_f32 v[114:115], v18, off offset:640
.LBB0_932:
	s_or_b64 exec, exec, s[34:35]
	s_waitcnt vmcnt(22)
	v_lshlrev_b32_e32 v18, 16, v130
	s_waitcnt lgkmcnt(0)
	v_and_b32_e32 v19, 0xffff0000, v130
	v_lshlrev_b32_e32 v20, 16, v131
	v_and_b32_e32 v21, 0xffff0000, v131
	v_pk_add_f32 v[16:17], v[16:17], v[20:21]
	v_pk_add_f32 v[14:15], v[14:15], v[18:19]
	v_lshlrev_b32_e32 v18, 16, v132
	v_and_b32_e32 v19, 0xffff0000, v132
	v_lshlrev_b32_e32 v20, 16, v133
	v_and_b32_e32 v21, 0xffff0000, v133
	v_pk_add_f32 v[20:21], v[12:13], v[20:21]
	v_pk_add_f32 v[18:19], v[10:11], v[18:19]
	v_cvt_pk_bf16_f32 v10, v14, v15
	v_cvt_pk_bf16_f32 v11, v16, v17
	v_lshl_add_u64 v[22:23], s[16:17], 0, v[210:211]
	v_cvt_pk_bf16_f32 v12, v18, v19
	v_cvt_pk_bf16_f32 v13, v20, v21
	v_lshl_add_u64 v[22:23], v[208:209], 1, v[22:23]
	global_store_dwordx4 v[22:23], v[10:13], off offset:0 sc1
	s_nop 1
	v_mul_f32_e32 v10, v15, v15
	v_mul_f32_e32 v11, v17, v17
	v_fmac_f32_e32 v10, v14, v14
	v_fmac_f32_e32 v11, v16, v16
	v_add_f32_e32 v10, v10, v11
	v_mul_f32_e32 v11, v19, v19
	v_mul_f32_e32 v12, v21, v21
	v_fmac_f32_e32 v11, v18, v18
	v_fmac_f32_e32 v12, v20, v20
	v_add_f32_e32 v11, v11, v12
	v_add_f32_e32 v14, v10, v11
	s_waitcnt vmcnt(22)
	v_lshlrev_b32_e32 v10, 16, v118
	v_and_b32_e32 v11, 0xffff0000, v118
	v_lshlrev_b32_e32 v12, 16, v119
	v_and_b32_e32 v13, 0xffff0000, v119
	v_pk_add_f32 v[8:9], v[8:9], v[12:13]
	v_pk_add_f32 v[6:7], v[6:7], v[10:11]
	v_lshlrev_b32_e32 v12, 16, v121
	v_and_b32_e32 v13, 0xffff0000, v121
	v_lshlrev_b32_e32 v10, 16, v120
	v_and_b32_e32 v11, 0xffff0000, v120
	v_pk_add_f32 v[12:13], v[4:5], v[12:13]
	v_mul_f32_e32 v4, v7, v7
	v_mul_f32_e32 v5, v9, v9
	v_pk_add_f32 v[2:3], v[2:3], v[10:11]
	v_fmac_f32_e32 v4, v6, v6
	v_fmac_f32_e32 v5, v8, v8
	v_add_f32_e32 v4, v4, v5
	v_mul_f32_e32 v5, v3, v3
	v_mul_f32_e32 v10, v13, v13
	v_fmac_f32_e32 v5, v2, v2
	v_fmac_f32_e32 v10, v12, v12
	v_add_f32_e32 v5, v5, v10
	v_add_f32_e32 v4, v5, v4
	v_add_f32_e32 v10, v14, v4
	ds_bpermute_b32 v11, v116, v10
	v_cvt_pk_bf16_f32 v4, v6, v7
	v_cvt_pk_bf16_f32 v6, v2, v3
	v_cvt_pk_bf16_f32 v5, v8, v9
	v_cvt_pk_bf16_f32 v7, v12, v13
	s_waitcnt lgkmcnt(0)
	v_add_f32_e32 v2, v10, v11
	ds_bpermute_b32 v3, v117, v2
	global_store_dwordx4 v[22:23], v[4:7], off offset:0x100 sc1
	s_nop 1
	s_and_saveexec_b64 s[34:35], s[22:23]
	s_cbranch_execz .LBB0_934
	s_waitcnt lgkmcnt(0)
	v_add_f32_e32 v2, v2, v3
	global_atomic_add_f32 v[114:115], v2, off offset:704

.LBB0_956:
	v_lshl_add_u32 v194, s55, 8, v228
	v_lshl_or_b32 v212, s54, 8, v230
	v_ashrrev_i32_e32 v213, 31, v212
	v_ashrrev_i32_e32 v195, 31, v194
	v_lshl_add_u64 v[122:123], v[212:213], 1, s[10:11]
	v_lshlrev_b64 v[124:125], 11, v[194:195]
	v_lshl_add_u64 v[124:125], v[122:123], 0, v[124:125]
	global_load_dwordx4 v[190:193], v[124:125], off
	global_load_dwordx4 v[186:189], v[124:125], off offset:256
	v_or_b32_e32 v226, 16, v194
	v_ashrrev_i32_e32 v227, 31, v226
	v_lshlrev_b64 v[124:125], 11, v[226:227]
	v_lshl_add_u64 v[124:125], v[122:123], 0, v[124:125]
	global_load_dwordx4 v[182:185], v[124:125], off
	global_load_dwordx4 v[178:181], v[124:125], off offset:256
	v_or_b32_e32 v224, 32, v194
	v_ashrrev_i32_e32 v225, 31, v224
	v_lshlrev_b64 v[124:125], 11, v[224:225]
	v_lshl_add_u64 v[124:125], v[122:123], 0, v[124:125]
	global_load_dwordx4 v[174:177], v[124:125], off
	global_load_dwordx4 v[170:173], v[124:125], off offset:256
	v_or_b32_e32 v222, 48, v194
	v_ashrrev_i32_e32 v223, 31, v222
	v_lshlrev_b64 v[124:125], 11, v[222:223]
	v_lshl_add_u64 v[124:125], v[122:123], 0, v[124:125]
	global_load_dwordx4 v[166:169], v[124:125], off
	global_load_dwordx4 v[162:165], v[124:125], off offset:256
	v_add_u32_e32 v220, 0x80, v194
	v_ashrrev_i32_e32 v221, 31, v220
	v_lshlrev_b64 v[124:125], 11, v[220:221]
	v_lshl_add_u64 v[124:125], v[122:123], 0, v[124:125]
	global_load_dwordx4 v[158:161], v[124:125], off
	global_load_dwordx4 v[154:157], v[124:125], off offset:256
	v_add_u32_e32 v218, 0x90, v194
	v_ashrrev_i32_e32 v219, 31, v218
	v_lshlrev_b64 v[124:125], 11, v[218:219]
	v_lshl_add_u64 v[124:125], v[122:123], 0, v[124:125]
	global_load_dwordx4 v[150:153], v[124:125], off
	global_load_dwordx4 v[146:149], v[124:125], off offset:256
	v_add_u32_e32 v216, 0xa0, v194
	v_ashrrev_i32_e32 v217, 31, v216
	v_lshlrev_b64 v[124:125], 11, v[216:217]
	v_lshl_add_u64 v[124:125], v[122:123], 0, v[124:125]
	global_load_dwordx4 v[142:145], v[124:125], off
	global_load_dwordx4 v[134:137], v[124:125], off offset:256
	v_add_u32_e32 v214, 0xb0, v194
	v_ashrrev_i32_e32 v215, 31, v214
	v_lshlrev_b64 v[124:125], 11, v[214:215]
	v_lshl_add_u64 v[122:123], v[122:123], 0, v[124:125]
	global_load_dwordx4 v[138:141], v[122:123], off
	s_nop 0
	global_load_dwordx4 v[122:125], v[122:123], off offset:256
	v_lshlrev_b64 v[194:195], 10, v[194:195]
	v_lshl_add_u64 v[194:195], v[194:195], 0, v[212:213]
	s_mov_b64 s[24:25], -1
	s_andn2_b64 vcc, exec, s[6:7]
	s_waitcnt vmcnt(15)
	v_lshlrev_b32_e32 v198, 16, v190
	v_and_b32_e32 v199, 0xffff0000, v190
	v_lshlrev_b32_e32 v190, 16, v191
	v_and_b32_e32 v191, 0xffff0000, v191
	v_pk_add_f32 v[132:133], v[132:133], v[190:191]
	v_lshlrev_b32_e32 v190, 16, v192
	v_and_b32_e32 v191, 0xffff0000, v192
	v_pk_add_f32 v[130:131], v[130:131], v[198:199]
	v_lshlrev_b32_e32 v192, 16, v193
	v_and_b32_e32 v193, 0xffff0000, v193
	v_pk_add_f32 v[126:127], v[126:127], v[190:191]
	v_lshl_add_u64 v[190:191], v[194:195], 2, s[8:9]
	v_pk_add_f32 v[128:129], v[128:129], v[192:193]
	global_store_dwordx4 v[190:191], v[130:133], off nt
	global_store_dwordx4 v[190:191], v[126:129], off offset:16 nt
	s_nop 0
	v_cvt_pk_bf16_f32 v130, v130, v131
	v_cvt_pk_bf16_f32 v131, v132, v133
	v_cvt_pk_bf16_f32 v132, v126, v127
	v_cvt_pk_bf16_f32 v133, v128, v129
	v_lshl_add_u64 v[126:127], v[194:195], 1, s[10:11]
	global_store_dwordx4 v[126:127], v[130:133], off offset:0 sc1
	s_nop 1
	s_waitcnt vmcnt(17)
	v_lshlrev_b32_e32 v128, 16, v186
	v_and_b32_e32 v129, 0xffff0000, v186
	v_lshlrev_b32_e32 v130, 16, v187
	v_and_b32_e32 v131, 0xffff0000, v187
	v_pk_add_f32 v[120:121], v[120:121], v[130:131]
	v_pk_add_f32 v[118:119], v[118:119], v[128:129]
	v_lshlrev_b32_e32 v128, 16, v188
	v_and_b32_e32 v129, 0xffff0000, v188
	v_lshlrev_b32_e32 v130, 16, v189
	v_and_b32_e32 v131, 0xffff0000, v189
	v_pk_add_f32 v[116:117], v[116:117], v[130:131]
	v_pk_add_f32 v[114:115], v[114:115], v[128:129]
	global_store_dwordx4 v[190:191], v[118:121], off offset:512 nt
	global_store_dwordx4 v[190:191], v[114:117], off offset:528 nt
	s_nop 0
	v_cvt_pk_bf16_f32 v118, v118, v119
	v_cvt_pk_bf16_f32 v119, v120, v121
	v_cvt_pk_bf16_f32 v120, v114, v115
	v_cvt_pk_bf16_f32 v121, v116, v117
	v_lshlrev_b64 v[114:115], 10, v[226:227]
	s_waitcnt vmcnt(18)
	v_lshlrev_b32_e32 v116, 16, v182
	v_and_b32_e32 v117, 0xffff0000, v182
	global_store_dwordx4 v[126:127], v[118:121], off offset:0x100 sc1
	s_nop 1
	v_lshl_add_u64 v[114:115], v[114:115], 0, v[212:213]
	v_lshlrev_b32_e32 v118, 16, v183
	v_and_b32_e32 v119, 0xffff0000, v183
	v_pk_add_f32 v[110:111], v[110:111], v[116:117]
	v_lshlrev_b32_e32 v116, 16, v184
	v_and_b32_e32 v117, 0xffff0000, v184
	v_pk_add_f32 v[112:113], v[112:113], v[118:119]
	v_lshlrev_b32_e32 v118, 16, v185
	v_and_b32_e32 v119, 0xffff0000, v185
	v_pk_add_f32 v[106:107], v[106:107], v[116:117]
	v_lshl_add_u64 v[116:117], v[114:115], 2, s[8:9]
	v_pk_add_f32 v[108:109], v[108:109], v[118:119]
	global_store_dwordx4 v[116:117], v[110:113], off nt
	global_store_dwordx4 v[116:117], v[106:109], off offset:16 nt
	s_nop 0
	v_cvt_pk_bf16_f32 v110, v110, v111
	v_cvt_pk_bf16_f32 v111, v112, v113
	v_cvt_pk_bf16_f32 v112, v106, v107
	v_cvt_pk_bf16_f32 v113, v108, v109
	v_lshl_add_u64 v[106:107], v[114:115], 1, s[10:11]
	global_store_dwordx4 v[106:107], v[110:113], off offset:0 sc1
	s_nop 1
	s_waitcnt vmcnt(21)
	v_lshlrev_b32_e32 v108, 16, v178
	v_and_b32_e32 v109, 0xffff0000, v178
	v_lshlrev_b32_e32 v110, 16, v179
	v_and_b32_e32 v111, 0xffff0000, v179
	v_pk_add_f32 v[104:105], v[104:105], v[110:111]
	v_pk_add_f32 v[102:103], v[102:103], v[108:109]
	v_lshlrev_b32_e32 v108, 16, v180
	v_and_b32_e32 v109, 0xffff0000, v180
	v_lshlrev_b32_e32 v110, 16, v181
	v_and_b32_e32 v111, 0xffff0000, v181
	v_pk_add_f32 v[100:101], v[100:101], v[110:111]
	v_pk_add_f32 v[98:99], v[98:99], v[108:109]
	global_store_dwordx4 v[116:117], v[102:105], off offset:512 nt
	global_store_dwordx4 v[116:117], v[98:101], off offset:528 nt
	s_nop 0
	v_cvt_pk_bf16_f32 v102, v102, v103
	v_cvt_pk_bf16_f32 v103, v104, v105
	v_cvt_pk_bf16_f32 v104, v98, v99
	v_cvt_pk_bf16_f32 v105, v100, v101
	v_lshlrev_b64 v[98:99], 10, v[224:225]
	s_waitcnt vmcnt(22)
	v_lshlrev_b32_e32 v100, 16, v174
	v_and_b32_e32 v101, 0xffff0000, v174
	global_store_dwordx4 v[106:107], v[102:105], off offset:0x100 sc1
	s_nop 1
	v_lshl_add_u64 v[98:99], v[98:99], 0, v[212:213]
	v_lshlrev_b32_e32 v102, 16, v175
	v_and_b32_e32 v103, 0xffff0000, v175
	v_pk_add_f32 v[94:95], v[94:95], v[100:101]
	v_lshlrev_b32_e32 v100, 16, v176
	v_and_b32_e32 v101, 0xffff0000, v176
	v_pk_add_f32 v[96:97], v[96:97], v[102:103]
	v_lshlrev_b32_e32 v102, 16, v177
	v_and_b32_e32 v103, 0xffff0000, v177
	v_pk_add_f32 v[90:91], v[90:91], v[100:101]
	v_lshl_add_u64 v[100:101], v[98:99], 2, s[8:9]
	v_pk_add_f32 v[92:93], v[92:93], v[102:103]
	global_store_dwordx4 v[100:101], v[94:97], off nt
	global_store_dwordx4 v[100:101], v[90:93], off offset:16 nt
	s_nop 0
	v_cvt_pk_bf16_f32 v94, v94, v95
	v_cvt_pk_bf16_f32 v95, v96, v97
	v_cvt_pk_bf16_f32 v96, v90, v91
	v_cvt_pk_bf16_f32 v97, v92, v93
	v_lshl_add_u64 v[90:91], v[98:99], 1, s[10:11]
	global_store_dwordx4 v[90:91], v[94:97], off offset:0 sc1
	s_nop 1
	s_waitcnt vmcnt(25)
	v_lshlrev_b32_e32 v92, 16, v170
	v_and_b32_e32 v93, 0xffff0000, v170
	v_lshlrev_b32_e32 v94, 16, v171
	v_and_b32_e32 v95, 0xffff0000, v171
	v_pk_add_f32 v[88:89], v[88:89], v[94:95]
	v_pk_add_f32 v[86:87], v[86:87], v[92:93]
	v_lshlrev_b32_e32 v92, 16, v172
	v_and_b32_e32 v93, 0xffff0000, v172
	v_lshlrev_b32_e32 v94, 16, v173
	v_and_b32_e32 v95, 0xffff0000, v173
	v_pk_add_f32 v[84:85], v[84:85], v[94:95]
	v_pk_add_f32 v[82:83], v[82:83], v[92:93]
	global_store_dwordx4 v[100:101], v[86:89], off offset:512 nt
	global_store_dwordx4 v[100:101], v[82:85], off offset:528 nt
	s_nop 0
	v_cvt_pk_bf16_f32 v86, v86, v87
	v_cvt_pk_bf16_f32 v87, v88, v89
	v_cvt_pk_bf16_f32 v88, v82, v83
	v_cvt_pk_bf16_f32 v89, v84, v85
	v_lshlrev_b64 v[82:83], 10, v[222:223]
	s_waitcnt vmcnt(26)
	v_lshlrev_b32_e32 v84, 16, v166
	v_and_b32_e32 v85, 0xffff0000, v166
	global_store_dwordx4 v[90:91], v[86:89], off offset:0x100 sc1
	s_nop 1
	v_lshl_add_u64 v[82:83], v[82:83], 0, v[212:213]
	v_lshlrev_b32_e32 v86, 16, v167
	v_and_b32_e32 v87, 0xffff0000, v167
	v_pk_add_f32 v[78:79], v[78:79], v[84:85]
	v_lshlrev_b32_e32 v84, 16, v168
	v_and_b32_e32 v85, 0xffff0000, v168
	v_pk_add_f32 v[80:81], v[80:81], v[86:87]
	v_lshlrev_b32_e32 v86, 16, v169
	v_and_b32_e32 v87, 0xffff0000, v169
	v_pk_add_f32 v[74:75], v[74:75], v[84:85]
	v_lshl_add_u64 v[84:85], v[82:83], 2, s[8:9]
	v_pk_add_f32 v[76:77], v[76:77], v[86:87]
	global_store_dwordx4 v[84:85], v[78:81], off nt
	global_store_dwordx4 v[84:85], v[74:77], off offset:16 nt
	s_nop 0
	v_cvt_pk_bf16_f32 v78, v78, v79
	v_cvt_pk_bf16_f32 v79, v80, v81
	v_cvt_pk_bf16_f32 v80, v74, v75
	v_cvt_pk_bf16_f32 v81, v76, v77
	v_lshl_add_u64 v[74:75], v[82:83], 1, s[10:11]
	global_store_dwordx4 v[74:75], v[78:81], off offset:0 sc1
	s_nop 1
	s_waitcnt vmcnt(29)
	v_lshlrev_b32_e32 v76, 16, v162
	v_and_b32_e32 v77, 0xffff0000, v162
	v_lshlrev_b32_e32 v78, 16, v163
	v_and_b32_e32 v79, 0xffff0000, v163
	v_pk_add_f32 v[72:73], v[72:73], v[78:79]
	v_pk_add_f32 v[70:71], v[70:71], v[76:77]
	v_lshlrev_b32_e32 v76, 16, v164
	v_and_b32_e32 v77, 0xffff0000, v164
	v_lshlrev_b32_e32 v78, 16, v165
	v_and_b32_e32 v79, 0xffff0000, v165
	v_pk_add_f32 v[68:69], v[68:69], v[78:79]
	v_pk_add_f32 v[66:67], v[66:67], v[76:77]
	global_store_dwordx4 v[84:85], v[70:73], off offset:512 nt
	global_store_dwordx4 v[84:85], v[66:69], off offset:528 nt
	s_nop 0
	v_cvt_pk_bf16_f32 v70, v70, v71
	v_cvt_pk_bf16_f32 v71, v72, v73
	v_cvt_pk_bf16_f32 v72, v66, v67
	v_cvt_pk_bf16_f32 v73, v68, v69
	v_lshlrev_b64 v[66:67], 10, v[220:221]
	s_waitcnt vmcnt(30)
	v_lshlrev_b32_e32 v68, 16, v158
	v_and_b32_e32 v69, 0xffff0000, v158
	global_store_dwordx4 v[74:75], v[70:73], off offset:0x100 sc1
	s_nop 1
	v_lshl_add_u64 v[66:67], v[66:67], 0, v[212:213]
	v_lshlrev_b32_e32 v70, 16, v159
	v_and_b32_e32 v71, 0xffff0000, v159
	v_pk_add_f32 v[62:63], v[62:63], v[68:69]
	v_lshlrev_b32_e32 v68, 16, v160
	v_and_b32_e32 v69, 0xffff0000, v160
	v_pk_add_f32 v[64:65], v[64:65], v[70:71]
	v_lshlrev_b32_e32 v70, 16, v161
	v_and_b32_e32 v71, 0xffff0000, v161
	v_pk_add_f32 v[58:59], v[58:59], v[68:69]
	v_lshl_add_u64 v[68:69], v[66:67], 2, s[8:9]
	v_pk_add_f32 v[60:61], v[60:61], v[70:71]
	global_store_dwordx4 v[68:69], v[62:65], off nt
	global_store_dwordx4 v[68:69], v[58:61], off offset:16 nt
	s_nop 0
	v_cvt_pk_bf16_f32 v62, v62, v63
	v_cvt_pk_bf16_f32 v63, v64, v65
	v_cvt_pk_bf16_f32 v64, v58, v59
	v_cvt_pk_bf16_f32 v65, v60, v61
	v_lshl_add_u64 v[58:59], v[66:67], 1, s[10:11]
	global_store_dwordx4 v[58:59], v[62:65], off offset:0 sc1
	s_nop 1
	s_waitcnt vmcnt(33)
	v_lshlrev_b32_e32 v60, 16, v154
	v_and_b32_e32 v61, 0xffff0000, v154
	v_lshlrev_b32_e32 v62, 16, v155
	v_and_b32_e32 v63, 0xffff0000, v155
	v_pk_add_f32 v[56:57], v[56:57], v[62:63]
	v_pk_add_f32 v[54:55], v[54:55], v[60:61]
	v_lshlrev_b32_e32 v60, 16, v156
	v_and_b32_e32 v61, 0xffff0000, v156
	v_lshlrev_b32_e32 v62, 16, v157
	v_and_b32_e32 v63, 0xffff0000, v157
	v_pk_add_f32 v[52:53], v[52:53], v[62:63]
	v_pk_add_f32 v[50:51], v[50:51], v[60:61]
	global_store_dwordx4 v[68:69], v[54:57], off offset:512 nt
	global_store_dwordx4 v[68:69], v[50:53], off offset:528 nt
	s_nop 0
	v_cvt_pk_bf16_f32 v54, v54, v55
	v_cvt_pk_bf16_f32 v55, v56, v57
	v_cvt_pk_bf16_f32 v56, v50, v51
	v_cvt_pk_bf16_f32 v57, v52, v53
	v_lshlrev_b64 v[50:51], 10, v[218:219]
	s_waitcnt vmcnt(34)
	v_lshlrev_b32_e32 v52, 16, v150
	v_and_b32_e32 v53, 0xffff0000, v150
	global_store_dwordx4 v[58:59], v[54:57], off offset:0x100 sc1
	s_nop 1
	v_lshl_add_u64 v[50:51], v[50:51], 0, v[212:213]
	v_lshlrev_b32_e32 v54, 16, v151
	v_and_b32_e32 v55, 0xffff0000, v151
	v_pk_add_f32 v[46:47], v[46:47], v[52:53]
	v_lshlrev_b32_e32 v52, 16, v152
	v_and_b32_e32 v53, 0xffff0000, v152
	v_pk_add_f32 v[48:49], v[48:49], v[54:55]
	v_lshlrev_b32_e32 v54, 16, v153
	v_and_b32_e32 v55, 0xffff0000, v153
	v_pk_add_f32 v[42:43], v[42:43], v[52:53]
	v_lshl_add_u64 v[52:53], v[50:51], 2, s[8:9]
	v_pk_add_f32 v[44:45], v[44:45], v[54:55]
	global_store_dwordx4 v[52:53], v[46:49], off nt
	global_store_dwordx4 v[52:53], v[42:45], off offset:16 nt
	s_nop 0
	v_cvt_pk_bf16_f32 v46, v46, v47
	v_cvt_pk_bf16_f32 v47, v48, v49
	v_cvt_pk_bf16_f32 v48, v42, v43
	v_cvt_pk_bf16_f32 v49, v44, v45
	v_lshl_add_u64 v[42:43], v[50:51], 1, s[10:11]
	global_store_dwordx4 v[42:43], v[46:49], off offset:0 sc1
	s_nop 1
	s_waitcnt vmcnt(37)
	v_lshlrev_b32_e32 v44, 16, v146
	v_and_b32_e32 v45, 0xffff0000, v146
	v_lshlrev_b32_e32 v46, 16, v147
	v_and_b32_e32 v47, 0xffff0000, v147
	v_pk_add_f32 v[40:41], v[40:41], v[46:47]
	v_pk_add_f32 v[38:39], v[38:39], v[44:45]
	v_lshlrev_b32_e32 v44, 16, v148
	v_and_b32_e32 v45, 0xffff0000, v148
	v_lshlrev_b32_e32 v46, 16, v149
	v_and_b32_e32 v47, 0xffff0000, v149
	v_pk_add_f32 v[36:37], v[36:37], v[46:47]
	v_pk_add_f32 v[34:35], v[34:35], v[44:45]
	global_store_dwordx4 v[52:53], v[38:41], off offset:512 nt
	global_store_dwordx4 v[52:53], v[34:37], off offset:528 nt
	s_nop 0
	v_cvt_pk_bf16_f32 v38, v38, v39
	v_cvt_pk_bf16_f32 v39, v40, v41
	v_cvt_pk_bf16_f32 v40, v34, v35
	v_cvt_pk_bf16_f32 v41, v36, v37
	v_lshlrev_b64 v[34:35], 10, v[216:217]
	s_waitcnt vmcnt(38)
	v_lshlrev_b32_e32 v36, 16, v142
	v_and_b32_e32 v37, 0xffff0000, v142
	global_store_dwordx4 v[42:43], v[38:41], off offset:0x100 sc1
	s_nop 1
	v_lshl_add_u64 v[34:35], v[34:35], 0, v[212:213]
	v_lshlrev_b32_e32 v38, 16, v143
	v_and_b32_e32 v39, 0xffff0000, v143
	v_pk_add_f32 v[30:31], v[30:31], v[36:37]
	v_lshlrev_b32_e32 v36, 16, v144
	v_and_b32_e32 v37, 0xffff0000, v144
	v_pk_add_f32 v[32:33], v[32:33], v[38:39]
	v_lshlrev_b32_e32 v38, 16, v145
	v_and_b32_e32 v39, 0xffff0000, v145
	v_pk_add_f32 v[26:27], v[26:27], v[36:37]
	v_lshl_add_u64 v[36:37], v[34:35], 2, s[8:9]
	v_pk_add_f32 v[28:29], v[28:29], v[38:39]
	global_store_dwordx4 v[36:37], v[30:33], off nt
	global_store_dwordx4 v[36:37], v[26:29], off offset:16 nt
	s_nop 0
	v_cvt_pk_bf16_f32 v30, v30, v31
	v_cvt_pk_bf16_f32 v31, v32, v33
	v_cvt_pk_bf16_f32 v32, v26, v27
	v_cvt_pk_bf16_f32 v33, v28, v29
	v_lshl_add_u64 v[26:27], v[34:35], 1, s[10:11]
	global_store_dwordx4 v[26:27], v[30:33], off offset:0 sc1
	s_nop 1
	s_waitcnt vmcnt(41)
	v_lshlrev_b32_e32 v28, 16, v134
	v_and_b32_e32 v29, 0xffff0000, v134
	v_lshlrev_b32_e32 v30, 16, v135
	v_and_b32_e32 v31, 0xffff0000, v135
	v_pk_add_f32 v[24:25], v[24:25], v[30:31]
	v_pk_add_f32 v[22:23], v[22:23], v[28:29]
	v_lshlrev_b32_e32 v28, 16, v136
	v_and_b32_e32 v29, 0xffff0000, v136
	v_lshlrev_b32_e32 v30, 16, v137
	v_and_b32_e32 v31, 0xffff0000, v137
	v_pk_add_f32 v[20:21], v[20:21], v[30:31]
	v_pk_add_f32 v[18:19], v[18:19], v[28:29]
	global_store_dwordx4 v[36:37], v[22:25], off offset:512 nt
	global_store_dwordx4 v[36:37], v[18:21], off offset:528 nt
	s_nop 0
	v_cvt_pk_bf16_f32 v22, v22, v23
	v_cvt_pk_bf16_f32 v23, v24, v25
	v_cvt_pk_bf16_f32 v24, v18, v19
	v_cvt_pk_bf16_f32 v25, v20, v21
	v_lshlrev_b64 v[18:19], 10, v[214:215]
	s_waitcnt vmcnt(42)
	v_lshlrev_b32_e32 v20, 16, v138
	v_and_b32_e32 v21, 0xffff0000, v138
	global_store_dwordx4 v[26:27], v[22:25], off offset:0x100 sc1
	s_nop 1
	v_lshl_add_u64 v[18:19], v[18:19], 0, v[212:213]
	v_lshlrev_b32_e32 v22, 16, v139
	v_and_b32_e32 v23, 0xffff0000, v139
	v_pk_add_f32 v[14:15], v[14:15], v[20:21]
	v_lshlrev_b32_e32 v20, 16, v140
	v_and_b32_e32 v21, 0xffff0000, v140
	v_pk_add_f32 v[16:17], v[16:17], v[22:23]
	v_lshlrev_b32_e32 v22, 16, v141
	v_and_b32_e32 v23, 0xffff0000, v141
	v_pk_add_f32 v[10:11], v[10:11], v[20:21]
	v_lshl_add_u64 v[20:21], v[18:19], 2, s[8:9]
	v_pk_add_f32 v[12:13], v[12:13], v[22:23]
	global_store_dwordx4 v[20:21], v[14:17], off nt
	global_store_dwordx4 v[20:21], v[10:13], off offset:16 nt
	s_nop 0
	v_cvt_pk_bf16_f32 v14, v14, v15
	v_cvt_pk_bf16_f32 v15, v16, v17
	v_cvt_pk_bf16_f32 v16, v10, v11
	v_cvt_pk_bf16_f32 v17, v12, v13
	v_lshl_add_u64 v[10:11], v[18:19], 1, s[10:11]
	global_store_dwordx4 v[10:11], v[14:17], off offset:0 sc1
	s_nop 1
	s_waitcnt vmcnt(45)
	v_lshlrev_b32_e32 v12, 16, v122
	v_and_b32_e32 v13, 0xffff0000, v122
	v_lshlrev_b32_e32 v14, 16, v123
	v_and_b32_e32 v15, 0xffff0000, v123
	v_pk_add_f32 v[8:9], v[8:9], v[14:15]
	v_pk_add_f32 v[6:7], v[6:7], v[12:13]
	v_lshlrev_b32_e32 v12, 16, v124
	v_and_b32_e32 v13, 0xffff0000, v124
	v_lshlrev_b32_e32 v14, 16, v125
	v_and_b32_e32 v15, 0xffff0000, v125
	v_pk_add_f32 v[4:5], v[4:5], v[14:15]
	v_pk_add_f32 v[2:3], v[2:3], v[12:13]
	global_store_dwordx4 v[20:21], v[6:9], off offset:512 nt
	global_store_dwordx4 v[20:21], v[2:5], off offset:528 nt
	s_nop 0
	v_cvt_pk_bf16_f32 v6, v6, v7
	v_cvt_pk_bf16_f32 v7, v8, v9
	v_cvt_pk_bf16_f32 v8, v2, v3
	v_cvt_pk_bf16_f32 v9, v4, v5
	global_store_dwordx4 v[10:11], v[6:9], off offset:0x100 sc1
	s_nop 1
	s_cbranch_vccnz .LBB0_945
	s_andn2_b64 vcc, exec, s[12:13]
	s_cbranch_vccnz .LBB0_944
	s_barrier
	s_branch .LBB0_944
